# sample-group GLA state loop pipelined: 8-channel groups, two load rings in flight, stores one group late, load-counted vmcnt (on top of previous best)
# speedup vs baseline: 1.0151x; 1.0057x over previous
; __device__ __forceinline__ void gla_sample_item(Frame& F, int item) {
;     ...
;     __syncthreads();
;     { const int dv = t; float v[16], o[16];
; #pragma unroll
;       for (int s = 0; s < 16; ++s) v[s] = bf2f(GV[(size_t)(m0 + s) * 2048 + h * 512 + dv]);
; #pragma unroll
;       for (int ti = 0; ti < 16; ++ti) { float a = 0.f;
; #pragma unroll
;           for (int s = 0; s < 16; ++s) a = fmaf(Am[ti * 16 + s], v[s], a);
;           o[ti] = a; }
.LBB0_1129:
	s_or_b64 exec, exec, s[0:1]
	v_readlane_b32 s0, v254, 21
	v_readlane_b32 s1, v254, 22
	s_or_b32 s14, s10, 0x4001
	s_or_b32 s13, s10, 0x4002
	v_lshl_add_u64 v[32:33], v[2:3], 1, s[0:1]
	s_lshl_b32 s1, s8, 12
	s_lshl_b32 s0, s11, 10
	s_or_b32 s46, s1, s0
	s_lshl_b32 s1, s14, 12
	v_lshl_add_u64 v[4:5], v[32:33], 0, s[46:47]
	s_or_b32 s46, s1, s0
	s_lshl_b32 s1, s13, 12
	s_waitcnt lgkmcnt(0)
	s_barrier
	global_load_ushort v0, v[4:5], off
	v_lshl_add_u64 v[4:5], v[32:33], 0, s[46:47]
	s_or_b32 s46, s1, s0
	v_lshl_add_u64 v[6:7], v[32:33], 0, s[46:47]
	global_load_ushort v4, v[4:5], off
	s_or_b32 s12, s10, 0x4003
	global_load_ushort v5, v[6:7], off
	s_lshl_b32 s1, s12, 12
	s_or_b32 s46, s1, s0
	v_lshl_add_u64 v[8:9], v[32:33], 0, s[46:47]
	s_lshl_b32 s6, s11, 9
	s_or_b32 s11, s10, 0x4004
	s_lshl_b32 s1, s11, 12
	s_or_b32 s46, s1, s0
	v_lshl_add_u64 v[10:11], v[32:33], 0, s[46:47]
	s_or_b32 s7, s10, 0x4005
	s_lshl_b32 s1, s7, 12
	s_or_b32 s46, s1, s0
	v_lshl_add_u64 v[12:13], v[32:33], 0, s[46:47]
	s_or_b32 s5, s10, 0x4006
	s_lshl_b32 s1, s5, 12
	s_or_b32 s46, s1, s0
	v_lshl_add_u64 v[14:15], v[32:33], 0, s[46:47]
	s_or_b32 s4, s10, 0x4007
	s_lshl_b32 s1, s4, 12
	s_or_b32 s46, s1, s0
	v_lshl_add_u64 v[16:17], v[32:33], 0, s[46:47]
	s_or_b32 s20, s10, 0x4008
	s_lshl_b32 s1, s20, 12
	s_or_b32 s46, s1, s0
	v_lshl_add_u64 v[18:19], v[32:33], 0, s[46:47]
	s_or_b32 s19, s10, 0x4009
	s_lshl_b32 s1, s19, 12
	s_or_b32 s46, s1, s0
	v_lshl_add_u64 v[20:21], v[32:33], 0, s[46:47]
	s_or_b32 s18, s10, 0x400a
	s_lshl_b32 s1, s18, 12
	s_or_b32 s46, s1, s0
	v_lshl_add_u64 v[22:23], v[32:33], 0, s[46:47]
	s_or_b32 s17, s10, 0x400b
	s_lshl_b32 s1, s17, 12
	s_or_b32 s46, s1, s0
	v_lshl_add_u64 v[24:25], v[32:33], 0, s[46:47]
	s_or_b32 s16, s9, 0x400c
	s_lshl_b32 s1, s16, 12
	s_or_b32 s46, s1, s0
	v_lshl_add_u64 v[26:27], v[32:33], 0, s[46:47]
	s_or_b32 s15, s9, 0x400d
	s_lshl_b32 s1, s15, 12
	s_or_b32 s46, s1, s0
	v_lshl_add_u64 v[28:29], v[32:33], 0, s[46:47]
	s_or_b32 s10, s9, 0x400e
	s_lshl_b32 s1, s10, 12
	s_or_b32 s46, s1, s0
	v_lshl_add_u64 v[30:31], v[32:33], 0, s[46:47]
	s_or_b32 s9, s9, 0x400f
	s_lshl_b32 s1, s9, 12
	s_or_b32 s46, s1, s0
	v_lshl_add_u64 v[32:33], v[32:33], 0, s[46:47]
	s_add_i32 s0, 0, 0x10010
	v_readlane_b32 s24, v253, 32
	v_readlane_b32 s64, v253, 0
	v_readlane_b32 s25, v253, 33
	v_readlane_b32 s72, v253, 8
	v_readlane_b32 s73, v253, 9
	s_mov_b32 s21, 0
	s_add_i32 s2, 0, 0x10404
	v_readlane_b32 s26, v253, 34
	v_readlane_b32 s27, v253, 35
	v_readlane_b32 s65, v253, 1
	v_readlane_b32 s66, v253, 2
	v_readlane_b32 s67, v253, 3
	v_readlane_b32 s68, v253, 4
	v_readlane_b32 s69, v253, 5
	v_readlane_b32 s70, v253, 6
	v_readlane_b32 s71, v253, 7
	v_readlane_b32 s74, v253, 10
	v_readlane_b32 s75, v253, 11
	v_readlane_b32 s76, v253, 12
	v_readlane_b32 s77, v253, 13
	s_waitcnt vmcnt(2)
	v_lshlrev_b32_e32 v0, 16, v0
	v_readlane_b32 s78, v253, 14
	v_readlane_b32 s79, v253, 15
	s_waitcnt vmcnt(1)
	v_lshlrev_b32_e32 v4, 16, v4
	s_waitcnt vmcnt(0)
	v_lshlrev_b32_e32 v6, 16, v5
	global_load_ushort v5, v[8:9], off
	s_waitcnt vmcnt(0)
	v_lshlrev_b32_e32 v8, 16, v5
	global_load_ushort v5, v[10:11], off
	s_waitcnt vmcnt(0)
	v_lshlrev_b32_e32 v10, 16, v5
	global_load_ushort v5, v[12:13], off
	s_waitcnt vmcnt(0)
	v_lshlrev_b32_e32 v12, 16, v5
	global_load_ushort v5, v[14:15], off
	s_waitcnt vmcnt(0)
	v_lshlrev_b32_e32 v14, 16, v5
	global_load_ushort v5, v[16:17], off
	s_waitcnt vmcnt(0)
	v_lshlrev_b32_e32 v16, 16, v5
	global_load_ushort v5, v[18:19], off
	s_waitcnt vmcnt(0)
	v_lshlrev_b32_e32 v18, 16, v5
	global_load_ushort v5, v[20:21], off
	s_waitcnt vmcnt(0)
	v_lshlrev_b32_e32 v20, 16, v5
	global_load_ushort v5, v[22:23], off
	s_waitcnt vmcnt(0)
	v_lshlrev_b32_e32 v22, 16, v5
	global_load_ushort v5, v[24:25], off
	s_waitcnt vmcnt(0)
	v_lshlrev_b32_e32 v24, 16, v5
	global_load_ushort v5, v[26:27], off
	s_waitcnt vmcnt(0)
	v_lshlrev_b32_e32 v26, 16, v5
	global_load_ushort v5, v[28:29], off
	s_waitcnt vmcnt(0)
	v_lshlrev_b32_e32 v28, 16, v5
	global_load_ushort v5, v[30:31], off
	s_waitcnt vmcnt(0)
	v_lshlrev_b32_e32 v30, 16, v5
	global_load_ushort v5, v[32:33], off
	s_waitcnt vmcnt(0)
	v_lshlrev_b32_e32 v32, 16, v5
	v_mov_b32_e32 v5, s0
	s_add_i32 s0, 0, 0x1003c
	ds_read_b96 v[44:46], v5
	v_mov_b32_e32 v5, s0
	s_add_i32 s0, 0, 0x10050
	ds_read_b32 v34, v5
	v_mov_b32_e32 v5, s0
	s_add_i32 s0, 0, 0x10000
	ds_read_b96 v[48:50], v5
	v_mov_b32_e32 v5, s0
	s_add_i32 s0, 0, 0x10040
	ds_read_b128 v[36:39], v5
	v_mov_b32_e32 v5, s0
	ds_read_b128 v[40:43], v5
	s_add_i32 s0, 0, 0x10074
	s_waitcnt lgkmcnt(1)
	v_mov_b32_e32 v52, v36
	s_waitcnt lgkmcnt(0)
	v_mov_b32_e32 v53, v40
	v_pk_fma_f32 v[52:53], v[52:53], v[0:1], 0 op_sel_hi:[1,0,0]
	v_mov_b32_e32 v40, v37
	v_pk_fma_f32 v[36:37], v[40:41], v[4:5], v[52:53] op_sel_hi:[1,0,1]
	v_mov_b32_e32 v40, v38
	v_mov_b32_e32 v41, v42
	v_pk_fma_f32 v[36:37], v[40:41], v[6:7], v[36:37] op_sel_hi:[1,0,1]
	v_mov_b32_e32 v42, v39
	v_pk_fma_f32 v[36:37], v[42:43], v[8:9], v[36:37] op_sel_hi:[1,0,1]
	v_mov_b32_e32 v38, v44
	v_mov_b32_e32 v39, v48
	v_mov_b32_e32 v5, s0
	s_add_i32 s0, 0, 0x1001c
	v_pk_fma_f32 v[36:37], v[38:39], v[10:11], v[36:37] op_sel_hi:[1,0,1]
	ds_read_b32 v39, v5
	v_mov_b32_e32 v5, s0
	s_add_i32 s0, 0, 0x10024
	ds_read2_b32 v[40:41], v5 offset1:1
	v_mov_b32_e32 v5, s0
	s_add_i32 s0, 0, 0x1002c
	ds_read2_b32 v[42:43], v5 offset1:1
	v_mov_b32_e32 v5, s0
	s_add_i32 s0, 0, 0x10034
	ds_read2_b32 v[52:53], v5 offset1:1
	v_mov_b32_e32 v5, s0
	v_mov_b32_e32 v48, v45
	s_add_i32 s0, 0, 0x1005c
	ds_read2_b32 v[54:55], v5 offset1:1
	v_pk_fma_f32 v[36:37], v[48:49], v[12:13], v[36:37] op_sel_hi:[1,0,1]
	v_mov_b32_e32 v44, v46
	v_mov_b32_e32 v45, v50
	v_mov_b32_e32 v5, s0
	v_pk_fma_f32 v[36:37], v[44:45], v[14:15], v[36:37] op_sel_hi:[1,0,1]
	ds_read2_b32 v[44:45], v5 offset1:1
	s_add_i32 s0, 0, 0x10064
	v_mov_b32_e32 v5, s0
	s_waitcnt lgkmcnt(4)
; __device__ __forceinline__ void gla_sample_item(Frame& F, int item) {
;     ...
;       for (int ti = 0; ti < 16; ++ti) { float a = 0.f;
; #pragma unroll
;           for (int s = 0; s < 16; ++s) a = fmaf(Am[ti * 16 + s], v[s], a);
;           o[ti] = a; }
	v_mov_b32_e32 v46, v40
	s_add_i32 s0, 0, 0x1006c
	s_waitcnt lgkmcnt(0)
	v_mov_b32_e32 v47, v44
	v_mov_b32_e32 v44, v41
	ds_read2_b32 v[40:41], v5 offset1:1
	v_pk_fma_f32 v[36:37], v[46:47], v[16:17], v[36:37] op_sel_hi:[1,0,1]
	v_mov_b32_e32 v5, s0
	v_pk_fma_f32 v[36:37], v[44:45], v[18:19], v[36:37] op_sel_hi:[1,0,1]
	v_mov_b32_e32 v44, v42
	s_waitcnt lgkmcnt(0)
	v_mov_b32_e32 v45, v40
	v_pk_fma_f32 v[36:37], v[44:45], v[20:21], v[36:37] op_sel_hi:[1,0,1]
	v_mov_b32_e32 v40, v43
	v_pk_fma_f32 v[36:37], v[40:41], v[22:23], v[36:37] op_sel_hi:[1,0,1]
	ds_read2_b32 v[40:41], v5 offset1:1
	v_mov_b32_e32 v42, v52
	s_add_i32 s0, 0, 0x10078
	v_mov_b32_e32 v38, v54
	v_mov_b32_e32 v5, s0
	s_waitcnt lgkmcnt(0)
	v_mov_b32_e32 v43, v40
	v_pk_fma_f32 v[36:37], v[42:43], v[24:25], v[36:37] op_sel_hi:[1,0,1]
	v_mov_b32_e32 v40, v53
	v_pk_fma_f32 v[36:37], v[40:41], v[26:27], v[36:37] op_sel_hi:[1,0,1]
	s_add_i32 s0, 0, 0x10090
	v_pk_fma_f32 v[40:41], v[38:39], v[28:29], v[36:37] op_sel_hi:[1,0,1]
	ds_read2_b64 v[36:39], v5 offset1:1
	v_mov_b32_e32 v5, s0
	s_add_i32 s0, 0, 0x100bc
	ds_read_b96 v[44:46], v5
	v_mov_b32_e32 v5, s0
	s_add_i32 s0, 0, 0x100d0
	s_waitcnt lgkmcnt(1)
	v_mov_b32_e32 v43, v36
	ds_read_b32 v36, v5
	v_mov_b32_e32 v5, s0
	s_add_i32 s0, 0, 0x10088
	v_mov_b32_e32 v42, v55
	ds_read_b96 v[48:50], v5
	v_mov_b32_e32 v5, s0
	s_add_i32 s0, 0, 0x100c0
	v_pk_fma_f32 v[40:41], v[42:43], v[30:31], v[40:41] op_sel_hi:[1,0,1]
	v_mov_b32_e32 v35, v37
	ds_read_b64 v[52:53], v5
	v_mov_b32_e32 v5, s0
	v_pk_fma_f32 v[34:35], v[34:35], v[32:33], v[40:41] op_sel_hi:[1,0,1]
	ds_read_b128 v[40:43], v5
	v_mov_b32_e32 v54, v38
	s_add_i32 s0, 0, 0x100f4
	s_waitcnt lgkmcnt(0)
	v_mov_b32_e32 v55, v40
	v_pk_fma_f32 v[54:55], v[54:55], v[0:1], 0 op_sel_hi:[1,0,0]
	v_mov_b32_e32 v40, v39
	v_pk_fma_f32 v[38:39], v[40:41], v[4:5], v[54:55] op_sel_hi:[1,0,1]
	v_mov_b32_e32 v40, v52
	v_mov_b32_e32 v41, v42
	v_pk_fma_f32 v[38:39], v[40:41], v[6:7], v[38:39] op_sel_hi:[1,0,1]
	v_mov_b32_e32 v42, v53
	v_pk_fma_f32 v[38:39], v[42:43], v[8:9], v[38:39] op_sel_hi:[1,0,1]
	v_mov_b32_e32 v40, v44
	v_mov_b32_e32 v41, v48
	v_mov_b32_e32 v5, s0
	s_add_i32 s0, 0, 0x1009c
	v_pk_fma_f32 v[38:39], v[40:41], v[10:11], v[38:39] op_sel_hi:[1,0,1]
	ds_read_b32 v41, v5
	v_mov_b32_e32 v5, s0
	s_add_i32 s0, 0, 0x100a4
	ds_read2_b32 v[42:43], v5 offset1:1
	v_mov_b32_e32 v5, s0
	s_add_i32 s0, 0, 0x100ac
	ds_read2_b32 v[52:53], v5 offset1:1
	v_mov_b32_e32 v5, s0
	s_add_i32 s0, 0, 0x100b4
	ds_read2_b32 v[54:55], v5 offset1:1
	v_mov_b32_e32 v5, s0
	v_mov_b32_e32 v48, v45
	s_add_i32 s0, 0, 0x100dc
	ds_read2_b32 v[56:57], v5 offset1:1
	v_pk_fma_f32 v[38:39], v[48:49], v[12:13], v[38:39] op_sel_hi:[1,0,1]
	v_mov_b32_e32 v44, v46
	v_mov_b32_e32 v45, v50
	v_mov_b32_e32 v5, s0
	v_pk_fma_f32 v[38:39], v[44:45], v[14:15], v[38:39] op_sel_hi:[1,0,1]
	ds_read2_b32 v[44:45], v5 offset1:1
	s_add_i32 s0, 0, 0x100e4
	v_mov_b32_e32 v5, s0
	s_waitcnt lgkmcnt(4)
	v_mov_b32_e32 v46, v42
	s_add_i32 s0, 0, 0x100ec
	s_waitcnt lgkmcnt(0)
	v_mov_b32_e32 v47, v44
	v_mov_b32_e32 v44, v43
	ds_read2_b32 v[42:43], v5 offset1:1
	v_pk_fma_f32 v[38:39], v[46:47], v[16:17], v[38:39] op_sel_hi:[1,0,1]
	v_mov_b32_e32 v5, s0
	v_pk_fma_f32 v[38:39], v[44:45], v[18:19], v[38:39] op_sel_hi:[1,0,1]
	v_mov_b32_e32 v44, v52
	s_waitcnt lgkmcnt(0)
	v_mov_b32_e32 v45, v42
	v_pk_fma_f32 v[38:39], v[44:45], v[20:21], v[38:39] op_sel_hi:[1,0,1]
	v_mov_b32_e32 v42, v53
	v_pk_fma_f32 v[38:39], v[42:43], v[22:23], v[38:39] op_sel_hi:[1,0,1]
	ds_read2_b32 v[42:43], v5 offset1:1
	v_mov_b32_e32 v44, v54
	s_add_i32 s0, 0, 0x100f8
	v_mov_b32_e32 v40, v56
	v_mov_b32_e32 v5, s0
	s_waitcnt lgkmcnt(0)
	v_mov_b32_e32 v45, v42
	v_pk_fma_f32 v[38:39], v[44:45], v[24:25], v[38:39] op_sel_hi:[1,0,1]
	v_mov_b32_e32 v42, v55
	v_pk_fma_f32 v[38:39], v[42:43], v[26:27], v[38:39] op_sel_hi:[1,0,1]
	s_add_i32 s0, 0, 0x10110
	v_pk_fma_f32 v[42:43], v[40:41], v[28:29], v[38:39] op_sel_hi:[1,0,1]
	ds_read2_b64 v[38:41], v5 offset1:1
	v_mov_b32_e32 v5, s0
	s_add_i32 s0, 0, 0x1013c
	ds_read_b96 v[46:48], v5
	v_mov_b32_e32 v5, s0
	s_add_i32 s0, 0, 0x10150
	s_waitcnt lgkmcnt(1)
	v_mov_b32_e32 v45, v38
	ds_read_b32 v38, v5
	v_mov_b32_e32 v5, s0
	s_add_i32 s0, 0, 0x10108
	v_mov_b32_e32 v44, v57
	ds_read_b96 v[50:52], v5
	v_mov_b32_e32 v5, s0
	s_add_i32 s0, 0, 0x10140
	v_pk_fma_f32 v[42:43], v[44:45], v[30:31], v[42:43] op_sel_hi:[1,0,1]
	v_mov_b32_e32 v37, v39
	ds_read_b64 v[54:55], v5
	v_mov_b32_e32 v5, s0
	v_pk_fma_f32 v[36:37], v[36:37], v[32:33], v[42:43] op_sel_hi:[1,0,1]
	ds_read_b128 v[42:45], v5
	v_mov_b32_e32 v56, v40
	s_add_i32 s0, 0, 0x10174
	s_waitcnt lgkmcnt(0)
	v_mov_b32_e32 v57, v42
	v_pk_fma_f32 v[56:57], v[56:57], v[0:1], 0 op_sel_hi:[1,0,0]
	v_mov_b32_e32 v42, v41
	v_pk_fma_f32 v[40:41], v[42:43], v[4:5], v[56:57] op_sel_hi:[1,0,1]
	v_mov_b32_e32 v42, v54
	v_mov_b32_e32 v43, v44
	v_pk_fma_f32 v[40:41], v[42:43], v[6:7], v[40:41] op_sel_hi:[1,0,1]
	v_mov_b32_e32 v44, v55
	v_pk_fma_f32 v[40:41], v[44:45], v[8:9], v[40:41] op_sel_hi:[1,0,1]
	v_mov_b32_e32 v42, v46
	v_mov_b32_e32 v43, v50
	v_mov_b32_e32 v5, s0
	s_add_i32 s0, 0, 0x1011c
	v_pk_fma_f32 v[40:41], v[42:43], v[10:11], v[40:41] op_sel_hi:[1,0,1]
	ds_read_b32 v43, v5
	v_mov_b32_e32 v5, s0
	s_add_i32 s0, 0, 0x10124
	ds_read2_b32 v[44:45], v5 offset1:1
	v_mov_b32_e32 v5, s0
	s_add_i32 s0, 0, 0x1012c
	ds_read2_b32 v[54:55], v5 offset1:1
	v_mov_b32_e32 v5, s0
	s_add_i32 s0, 0, 0x10134
	ds_read2_b32 v[56:57], v5 offset1:1
	v_mov_b32_e32 v5, s0
	v_mov_b32_e32 v50, v47
	s_add_i32 s0, 0, 0x1015c
	ds_read2_b32 v[58:59], v5 offset1:1
	v_pk_fma_f32 v[40:41], v[50:51], v[12:13], v[40:41] op_sel_hi:[1,0,1]
	v_mov_b32_e32 v46, v48
	v_mov_b32_e32 v47, v52
	v_mov_b32_e32 v5, s0
	v_pk_fma_f32 v[40:41], v[46:47], v[14:15], v[40:41] op_sel_hi:[1,0,1]
	ds_read2_b32 v[46:47], v5 offset1:1
	s_add_i32 s0, 0, 0x10164
	v_mov_b32_e32 v5, s0
	s_waitcnt lgkmcnt(4)
; __device__ __forceinline__ void gla_sample_item(Frame& F, int item) {
;     ...
;       for (int ti = 0; ti < 16; ++ti) { float a = 0.f;
; #pragma unroll
;           for (int s = 0; s < 16; ++s) a = fmaf(Am[ti * 16 + s], v[s], a);
;           o[ti] = a; }
	v_mov_b32_e32 v48, v44
	s_add_i32 s0, 0, 0x1016c
	s_waitcnt lgkmcnt(0)
	v_mov_b32_e32 v49, v46
	v_mov_b32_e32 v46, v45
	ds_read2_b32 v[44:45], v5 offset1:1
	v_pk_fma_f32 v[40:41], v[48:49], v[16:17], v[40:41] op_sel_hi:[1,0,1]
	v_mov_b32_e32 v5, s0
	v_pk_fma_f32 v[40:41], v[46:47], v[18:19], v[40:41] op_sel_hi:[1,0,1]
	v_mov_b32_e32 v46, v54
	s_waitcnt lgkmcnt(0)
	v_mov_b32_e32 v47, v44
	v_pk_fma_f32 v[40:41], v[46:47], v[20:21], v[40:41] op_sel_hi:[1,0,1]
	v_mov_b32_e32 v44, v55
	v_pk_fma_f32 v[40:41], v[44:45], v[22:23], v[40:41] op_sel_hi:[1,0,1]
	ds_read2_b32 v[44:45], v5 offset1:1
	v_mov_b32_e32 v46, v56
	s_add_i32 s0, 0, 0x10178
	v_mov_b32_e32 v42, v58
	v_mov_b32_e32 v5, s0
	s_waitcnt lgkmcnt(0)
	v_mov_b32_e32 v47, v44
	v_pk_fma_f32 v[40:41], v[46:47], v[24:25], v[40:41] op_sel_hi:[1,0,1]
	v_mov_b32_e32 v44, v57
	v_pk_fma_f32 v[40:41], v[44:45], v[26:27], v[40:41] op_sel_hi:[1,0,1]
	s_add_i32 s0, 0, 0x10190
	v_pk_fma_f32 v[44:45], v[42:43], v[28:29], v[40:41] op_sel_hi:[1,0,1]
	ds_read2_b64 v[40:43], v5 offset1:1
	v_mov_b32_e32 v5, s0
	s_add_i32 s0, 0, 0x101bc
	ds_read_b96 v[48:50], v5
	v_mov_b32_e32 v5, s0
	s_add_i32 s0, 0, 0x101d0
	s_waitcnt lgkmcnt(1)
	v_mov_b32_e32 v47, v40
	ds_read_b32 v40, v5
	v_mov_b32_e32 v5, s0
	s_add_i32 s0, 0, 0x10188
	v_mov_b32_e32 v46, v59
	ds_read_b96 v[52:54], v5
	v_mov_b32_e32 v5, s0
	s_add_i32 s0, 0, 0x101c0
	v_pk_fma_f32 v[44:45], v[46:47], v[30:31], v[44:45] op_sel_hi:[1,0,1]
	v_mov_b32_e32 v39, v41
	ds_read_b64 v[56:57], v5
	v_mov_b32_e32 v5, s0
	v_pk_fma_f32 v[38:39], v[38:39], v[32:33], v[44:45] op_sel_hi:[1,0,1]
	ds_read_b128 v[44:47], v5
	v_mov_b32_e32 v58, v42
	s_add_i32 s0, 0, 0x101f4
	s_waitcnt lgkmcnt(0)
	v_mov_b32_e32 v59, v44
	v_pk_fma_f32 v[58:59], v[58:59], v[0:1], 0 op_sel_hi:[1,0,0]
	v_mov_b32_e32 v44, v43
	v_pk_fma_f32 v[42:43], v[44:45], v[4:5], v[58:59] op_sel_hi:[1,0,1]
	v_mov_b32_e32 v44, v56
	v_mov_b32_e32 v45, v46
	v_pk_fma_f32 v[42:43], v[44:45], v[6:7], v[42:43] op_sel_hi:[1,0,1]
	v_mov_b32_e32 v46, v57
	v_pk_fma_f32 v[42:43], v[46:47], v[8:9], v[42:43] op_sel_hi:[1,0,1]
	v_mov_b32_e32 v44, v48
	v_mov_b32_e32 v45, v52
	v_mov_b32_e32 v5, s0
	s_add_i32 s0, 0, 0x1019c
	v_pk_fma_f32 v[42:43], v[44:45], v[10:11], v[42:43] op_sel_hi:[1,0,1]
	ds_read_b32 v45, v5
	v_mov_b32_e32 v5, s0
	s_add_i32 s0, 0, 0x101a4
	ds_read2_b32 v[46:47], v5 offset1:1
	v_mov_b32_e32 v5, s0
	s_add_i32 s0, 0, 0x101ac
	ds_read2_b32 v[56:57], v5 offset1:1
	v_mov_b32_e32 v5, s0
	s_add_i32 s0, 0, 0x101b4
	ds_read2_b32 v[58:59], v5 offset1:1
	v_mov_b32_e32 v5, s0
	v_mov_b32_e32 v52, v49
	s_add_i32 s0, 0, 0x101dc
	ds_read2_b32 v[60:61], v5 offset1:1
	v_pk_fma_f32 v[42:43], v[52:53], v[12:13], v[42:43] op_sel_hi:[1,0,1]
	v_mov_b32_e32 v48, v50
	v_mov_b32_e32 v49, v54
	v_mov_b32_e32 v5, s0
	v_pk_fma_f32 v[42:43], v[48:49], v[14:15], v[42:43] op_sel_hi:[1,0,1]
	ds_read2_b32 v[48:49], v5 offset1:1
	s_add_i32 s0, 0, 0x101e4
	v_mov_b32_e32 v5, s0
	s_waitcnt lgkmcnt(4)
	v_mov_b32_e32 v50, v46
	s_add_i32 s0, 0, 0x101ec
	s_waitcnt lgkmcnt(0)
	v_mov_b32_e32 v51, v48
	v_mov_b32_e32 v48, v47
	ds_read2_b32 v[46:47], v5 offset1:1
	v_pk_fma_f32 v[42:43], v[50:51], v[16:17], v[42:43] op_sel_hi:[1,0,1]
	v_mov_b32_e32 v5, s0
	v_pk_fma_f32 v[42:43], v[48:49], v[18:19], v[42:43] op_sel_hi:[1,0,1]
	v_mov_b32_e32 v48, v56
	s_waitcnt lgkmcnt(0)
	v_mov_b32_e32 v49, v46
	v_pk_fma_f32 v[42:43], v[48:49], v[20:21], v[42:43] op_sel_hi:[1,0,1]
	v_mov_b32_e32 v46, v57
	v_pk_fma_f32 v[42:43], v[46:47], v[22:23], v[42:43] op_sel_hi:[1,0,1]
	ds_read2_b32 v[46:47], v5 offset1:1
	v_mov_b32_e32 v48, v58
	s_add_i32 s0, 0, 0x101f8
	v_mov_b32_e32 v44, v60
	v_mov_b32_e32 v5, s0
	s_waitcnt lgkmcnt(0)
	v_mov_b32_e32 v49, v46
	v_pk_fma_f32 v[42:43], v[48:49], v[24:25], v[42:43] op_sel_hi:[1,0,1]
	v_mov_b32_e32 v46, v59
	v_pk_fma_f32 v[42:43], v[46:47], v[26:27], v[42:43] op_sel_hi:[1,0,1]
	s_add_i32 s0, 0, 0x10210
	v_pk_fma_f32 v[46:47], v[44:45], v[28:29], v[42:43] op_sel_hi:[1,0,1]
	ds_read2_b64 v[42:45], v5 offset1:1
	v_mov_b32_e32 v5, s0
	s_add_i32 s0, 0, 0x1023c
	ds_read_b96 v[50:52], v5
	v_mov_b32_e32 v5, s0
	s_add_i32 s0, 0, 0x10250
	s_waitcnt lgkmcnt(1)
	v_mov_b32_e32 v49, v42
	ds_read_b32 v42, v5
	v_mov_b32_e32 v5, s0
	s_add_i32 s0, 0, 0x10208
	v_mov_b32_e32 v48, v61
	ds_read_b96 v[54:56], v5
	v_mov_b32_e32 v5, s0
	s_add_i32 s0, 0, 0x10240
	v_pk_fma_f32 v[46:47], v[48:49], v[30:31], v[46:47] op_sel_hi:[1,0,1]
	v_mov_b32_e32 v41, v43
	ds_read_b64 v[58:59], v5
	v_mov_b32_e32 v5, s0
	v_pk_fma_f32 v[40:41], v[40:41], v[32:33], v[46:47] op_sel_hi:[1,0,1]
	ds_read_b128 v[46:49], v5
	v_mov_b32_e32 v60, v44
	s_add_i32 s0, 0, 0x10274
	s_waitcnt lgkmcnt(0)
	v_mov_b32_e32 v61, v46
	v_pk_fma_f32 v[60:61], v[60:61], v[0:1], 0 op_sel_hi:[1,0,0]
	v_mov_b32_e32 v46, v45
	v_pk_fma_f32 v[44:45], v[46:47], v[4:5], v[60:61] op_sel_hi:[1,0,1]
	v_mov_b32_e32 v46, v58
	v_mov_b32_e32 v47, v48
	v_pk_fma_f32 v[44:45], v[46:47], v[6:7], v[44:45] op_sel_hi:[1,0,1]
	v_mov_b32_e32 v48, v59
	v_pk_fma_f32 v[44:45], v[48:49], v[8:9], v[44:45] op_sel_hi:[1,0,1]
	v_mov_b32_e32 v46, v50
	v_mov_b32_e32 v47, v54
	v_mov_b32_e32 v5, s0
	s_add_i32 s0, 0, 0x1021c
	v_pk_fma_f32 v[44:45], v[46:47], v[10:11], v[44:45] op_sel_hi:[1,0,1]
	ds_read_b32 v47, v5
	v_mov_b32_e32 v5, s0
	s_add_i32 s0, 0, 0x10224
	ds_read2_b32 v[48:49], v5 offset1:1
	v_mov_b32_e32 v5, s0
	s_add_i32 s0, 0, 0x1022c
	ds_read2_b32 v[58:59], v5 offset1:1
	v_mov_b32_e32 v5, s0
	s_add_i32 s0, 0, 0x10234
	ds_read2_b32 v[60:61], v5 offset1:1
	v_mov_b32_e32 v5, s0
	v_mov_b32_e32 v54, v51
	s_add_i32 s0, 0, 0x1025c
	ds_read2_b32 v[62:63], v5 offset1:1
	v_pk_fma_f32 v[44:45], v[54:55], v[12:13], v[44:45] op_sel_hi:[1,0,1]
	v_mov_b32_e32 v50, v52
	v_mov_b32_e32 v51, v56
	v_mov_b32_e32 v5, s0
	v_pk_fma_f32 v[44:45], v[50:51], v[14:15], v[44:45] op_sel_hi:[1,0,1]
	ds_read2_b32 v[50:51], v5 offset1:1
	s_add_i32 s0, 0, 0x10264
	v_mov_b32_e32 v5, s0
	s_waitcnt lgkmcnt(4)
; __device__ __forceinline__ void gla_sample_item(Frame& F, int item) {
;     ...
;       for (int ti = 0; ti < 16; ++ti) { float a = 0.f;
; #pragma unroll
;           for (int s = 0; s < 16; ++s) a = fmaf(Am[ti * 16 + s], v[s], a);
;           o[ti] = a; }
	v_mov_b32_e32 v52, v48
	s_add_i32 s0, 0, 0x1026c
	s_waitcnt lgkmcnt(0)
	v_mov_b32_e32 v53, v50
	v_mov_b32_e32 v50, v49
	ds_read2_b32 v[48:49], v5 offset1:1
	v_pk_fma_f32 v[44:45], v[52:53], v[16:17], v[44:45] op_sel_hi:[1,0,1]
	v_mov_b32_e32 v5, s0
	v_pk_fma_f32 v[44:45], v[50:51], v[18:19], v[44:45] op_sel_hi:[1,0,1]
	v_mov_b32_e32 v50, v58
	s_waitcnt lgkmcnt(0)
	v_mov_b32_e32 v51, v48
	v_pk_fma_f32 v[44:45], v[50:51], v[20:21], v[44:45] op_sel_hi:[1,0,1]
	v_mov_b32_e32 v48, v59
	v_pk_fma_f32 v[44:45], v[48:49], v[22:23], v[44:45] op_sel_hi:[1,0,1]
	ds_read2_b32 v[48:49], v5 offset1:1
	v_mov_b32_e32 v50, v60
	s_add_i32 s0, 0, 0x10278
	v_mov_b32_e32 v46, v62
	v_mov_b32_e32 v5, s0
	s_waitcnt lgkmcnt(0)
	v_mov_b32_e32 v51, v48
	v_pk_fma_f32 v[44:45], v[50:51], v[24:25], v[44:45] op_sel_hi:[1,0,1]
	v_mov_b32_e32 v48, v61
	v_pk_fma_f32 v[44:45], v[48:49], v[26:27], v[44:45] op_sel_hi:[1,0,1]
	s_add_i32 s0, 0, 0x10290
	v_pk_fma_f32 v[48:49], v[46:47], v[28:29], v[44:45] op_sel_hi:[1,0,1]
	ds_read2_b64 v[44:47], v5 offset1:1
	v_mov_b32_e32 v5, s0
	s_add_i32 s0, 0, 0x102bc
	ds_read_b96 v[52:54], v5
	v_mov_b32_e32 v5, s0
	s_add_i32 s0, 0, 0x102d0
	s_waitcnt lgkmcnt(1)
	v_mov_b32_e32 v51, v44
	ds_read_b32 v44, v5
	v_mov_b32_e32 v5, s0
	s_add_i32 s0, 0, 0x10288
	v_mov_b32_e32 v50, v63
	ds_read_b96 v[56:58], v5
	v_mov_b32_e32 v5, s0
	s_add_i32 s0, 0, 0x102c0
	v_pk_fma_f32 v[48:49], v[50:51], v[30:31], v[48:49] op_sel_hi:[1,0,1]
	v_mov_b32_e32 v43, v45
	ds_read_b64 v[60:61], v5
	v_mov_b32_e32 v5, s0
	v_pk_fma_f32 v[42:43], v[42:43], v[32:33], v[48:49] op_sel_hi:[1,0,1]
	ds_read_b128 v[48:51], v5
	v_mov_b32_e32 v62, v46
	s_add_i32 s0, 0, 0x102f4
	s_waitcnt lgkmcnt(0)
	v_mov_b32_e32 v63, v48
	v_pk_fma_f32 v[62:63], v[62:63], v[0:1], 0 op_sel_hi:[1,0,0]
	v_mov_b32_e32 v48, v47
	v_pk_fma_f32 v[46:47], v[48:49], v[4:5], v[62:63] op_sel_hi:[1,0,1]
	v_mov_b32_e32 v48, v60
	v_mov_b32_e32 v49, v50
	v_pk_fma_f32 v[46:47], v[48:49], v[6:7], v[46:47] op_sel_hi:[1,0,1]
	v_mov_b32_e32 v50, v61
	v_pk_fma_f32 v[46:47], v[50:51], v[8:9], v[46:47] op_sel_hi:[1,0,1]
	v_mov_b32_e32 v48, v52
	v_mov_b32_e32 v49, v56
	v_mov_b32_e32 v5, s0
	s_add_i32 s0, 0, 0x1029c
	v_pk_fma_f32 v[46:47], v[48:49], v[10:11], v[46:47] op_sel_hi:[1,0,1]
	ds_read_b32 v49, v5
	v_mov_b32_e32 v5, s0
	s_add_i32 s0, 0, 0x102a4
	ds_read2_b32 v[50:51], v5 offset1:1
	v_mov_b32_e32 v5, s0
	s_add_i32 s0, 0, 0x102ac
	ds_read2_b32 v[60:61], v5 offset1:1
	v_mov_b32_e32 v5, s0
	s_add_i32 s0, 0, 0x102b4
	ds_read2_b32 v[62:63], v5 offset1:1
	v_mov_b32_e32 v5, s0
	v_mov_b32_e32 v56, v53
	s_add_i32 s0, 0, 0x102dc
	ds_read2_b32 v[64:65], v5 offset1:1
	v_pk_fma_f32 v[46:47], v[56:57], v[12:13], v[46:47] op_sel_hi:[1,0,1]
	v_mov_b32_e32 v52, v54
	v_mov_b32_e32 v53, v58
	v_mov_b32_e32 v5, s0
	v_pk_fma_f32 v[46:47], v[52:53], v[14:15], v[46:47] op_sel_hi:[1,0,1]
	ds_read2_b32 v[52:53], v5 offset1:1
	s_add_i32 s0, 0, 0x102e4
	v_mov_b32_e32 v5, s0
	s_waitcnt lgkmcnt(4)
	v_mov_b32_e32 v54, v50
	s_add_i32 s0, 0, 0x102ec
	s_waitcnt lgkmcnt(0)
	v_mov_b32_e32 v55, v52
	v_mov_b32_e32 v52, v51
	ds_read2_b32 v[50:51], v5 offset1:1
	v_pk_fma_f32 v[46:47], v[54:55], v[16:17], v[46:47] op_sel_hi:[1,0,1]
	v_mov_b32_e32 v5, s0
	v_pk_fma_f32 v[46:47], v[52:53], v[18:19], v[46:47] op_sel_hi:[1,0,1]
	v_mov_b32_e32 v52, v60
	s_waitcnt lgkmcnt(0)
	v_mov_b32_e32 v53, v50
	v_pk_fma_f32 v[46:47], v[52:53], v[20:21], v[46:47] op_sel_hi:[1,0,1]
	v_mov_b32_e32 v50, v61
	v_pk_fma_f32 v[46:47], v[50:51], v[22:23], v[46:47] op_sel_hi:[1,0,1]
	ds_read2_b32 v[50:51], v5 offset1:1
	v_mov_b32_e32 v52, v62
	s_add_i32 s0, 0, 0x102f8
	v_mov_b32_e32 v48, v64
	v_mov_b32_e32 v5, s0
	s_waitcnt lgkmcnt(0)
	v_mov_b32_e32 v53, v50
	v_pk_fma_f32 v[46:47], v[52:53], v[24:25], v[46:47] op_sel_hi:[1,0,1]
	v_mov_b32_e32 v50, v63
	v_pk_fma_f32 v[46:47], v[50:51], v[26:27], v[46:47] op_sel_hi:[1,0,1]
	s_add_i32 s0, 0, 0x10310
	v_pk_fma_f32 v[50:51], v[48:49], v[28:29], v[46:47] op_sel_hi:[1,0,1]
	ds_read2_b64 v[46:49], v5 offset1:1
	v_mov_b32_e32 v5, s0
	s_add_i32 s0, 0, 0x1033c
	ds_read_b96 v[54:56], v5
	v_mov_b32_e32 v5, s0
	s_add_i32 s0, 0, 0x10350
	s_waitcnt lgkmcnt(1)
	v_mov_b32_e32 v53, v46
	ds_read_b32 v46, v5
	v_mov_b32_e32 v5, s0
	s_add_i32 s0, 0, 0x10308
	v_mov_b32_e32 v52, v65
	ds_read_b96 v[58:60], v5
	v_mov_b32_e32 v5, s0
	s_add_i32 s0, 0, 0x10340
	v_pk_fma_f32 v[50:51], v[52:53], v[30:31], v[50:51] op_sel_hi:[1,0,1]
	v_mov_b32_e32 v45, v47
	ds_read_b64 v[62:63], v5
	v_mov_b32_e32 v5, s0
	v_pk_fma_f32 v[44:45], v[44:45], v[32:33], v[50:51] op_sel_hi:[1,0,1]
	ds_read_b128 v[50:53], v5
	v_mov_b32_e32 v64, v48
	s_add_i32 s0, 0, 0x10374
	s_waitcnt lgkmcnt(0)
	v_mov_b32_e32 v65, v50
	v_pk_fma_f32 v[64:65], v[64:65], v[0:1], 0 op_sel_hi:[1,0,0]
	v_mov_b32_e32 v50, v49
	v_pk_fma_f32 v[48:49], v[50:51], v[4:5], v[64:65] op_sel_hi:[1,0,1]
	v_mov_b32_e32 v50, v62
	v_mov_b32_e32 v51, v52
	v_pk_fma_f32 v[48:49], v[50:51], v[6:7], v[48:49] op_sel_hi:[1,0,1]
	v_mov_b32_e32 v52, v63
	v_pk_fma_f32 v[48:49], v[52:53], v[8:9], v[48:49] op_sel_hi:[1,0,1]
	v_mov_b32_e32 v50, v54
	v_mov_b32_e32 v51, v58
	v_mov_b32_e32 v5, s0
	s_add_i32 s0, 0, 0x1031c
	v_pk_fma_f32 v[48:49], v[50:51], v[10:11], v[48:49] op_sel_hi:[1,0,1]
	ds_read_b32 v51, v5
	v_mov_b32_e32 v5, s0
	s_add_i32 s0, 0, 0x10324
	ds_read2_b32 v[52:53], v5 offset1:1
	v_mov_b32_e32 v5, s0
	s_add_i32 s0, 0, 0x1032c
	ds_read2_b32 v[62:63], v5 offset1:1
	v_mov_b32_e32 v5, s0
	s_add_i32 s0, 0, 0x10334
	ds_read2_b32 v[64:65], v5 offset1:1
	v_mov_b32_e32 v5, s0
	v_mov_b32_e32 v58, v55
	s_add_i32 s0, 0, 0x1035c
	ds_read2_b32 v[66:67], v5 offset1:1
	v_pk_fma_f32 v[48:49], v[58:59], v[12:13], v[48:49] op_sel_hi:[1,0,1]
	v_mov_b32_e32 v54, v56
	v_mov_b32_e32 v55, v60
	v_mov_b32_e32 v5, s0
	v_pk_fma_f32 v[48:49], v[54:55], v[14:15], v[48:49] op_sel_hi:[1,0,1]
	ds_read2_b32 v[54:55], v5 offset1:1
	s_add_i32 s0, 0, 0x10364
	v_mov_b32_e32 v5, s0
	s_waitcnt lgkmcnt(4)
; __device__ __forceinline__ void gla_sample_item(Frame& F, int item) {
;     ...
;       for (int ti = 0; ti < 16; ++ti) { float a = 0.f;
; #pragma unroll
;           for (int s = 0; s < 16; ++s) a = fmaf(Am[ti * 16 + s], v[s], a);
;           o[ti] = a; }
;       const float* S0 = F.state + ((size_t)(sb * 4 + h) * 256) * 512 + dv; float* S1 = F.out + O_GS + ((size_t)(sb * 4 + h) * 256) * 512 + dv;
;       for (int chh = 0; chh < 256; ++chh) {
;           const float s0 = S0[(size_t)chh * 512];
	v_mov_b32_e32 v56, v52
	s_add_i32 s0, 0, 0x1036c
	s_waitcnt lgkmcnt(0)
	v_mov_b32_e32 v57, v54
	v_mov_b32_e32 v54, v53
	ds_read2_b32 v[52:53], v5 offset1:1
	v_pk_fma_f32 v[48:49], v[56:57], v[16:17], v[48:49] op_sel_hi:[1,0,1]
	v_mov_b32_e32 v5, s0
	v_pk_fma_f32 v[48:49], v[54:55], v[18:19], v[48:49] op_sel_hi:[1,0,1]
	v_mov_b32_e32 v54, v62
	s_waitcnt lgkmcnt(0)
	v_mov_b32_e32 v55, v52
	v_pk_fma_f32 v[48:49], v[54:55], v[20:21], v[48:49] op_sel_hi:[1,0,1]
	v_mov_b32_e32 v52, v63
	v_pk_fma_f32 v[48:49], v[52:53], v[22:23], v[48:49] op_sel_hi:[1,0,1]
	ds_read2_b32 v[52:53], v5 offset1:1
	v_mov_b32_e32 v54, v64
	s_add_i32 s0, 0, 0x10378
	v_mov_b32_e32 v50, v66
	v_mov_b32_e32 v5, s0
	s_waitcnt lgkmcnt(0)
	v_mov_b32_e32 v55, v52
	v_pk_fma_f32 v[48:49], v[54:55], v[24:25], v[48:49] op_sel_hi:[1,0,1]
	v_mov_b32_e32 v52, v65
	v_pk_fma_f32 v[48:49], v[52:53], v[26:27], v[48:49] op_sel_hi:[1,0,1]
	s_add_i32 s0, 0, 0x10390
	v_pk_fma_f32 v[52:53], v[50:51], v[28:29], v[48:49] op_sel_hi:[1,0,1]
	ds_read2_b64 v[48:51], v5 offset1:1
	v_mov_b32_e32 v5, s0
	s_add_i32 s0, 0, 0x103bc
	ds_read_b96 v[56:58], v5
	v_mov_b32_e32 v5, s0
	s_add_i32 s0, 0, 0x103d0
	s_waitcnt lgkmcnt(1)
	v_mov_b32_e32 v55, v48
	ds_read_b32 v48, v5
	v_mov_b32_e32 v5, s0
	s_add_i32 s0, 0, 0x10388
	v_mov_b32_e32 v54, v67
	ds_read_b96 v[60:62], v5
	v_mov_b32_e32 v5, s0
	s_add_i32 s0, 0, 0x103c0
	v_pk_fma_f32 v[52:53], v[54:55], v[30:31], v[52:53] op_sel_hi:[1,0,1]
	v_mov_b32_e32 v47, v49
	ds_read_b64 v[64:65], v5
	v_mov_b32_e32 v5, s0
	v_pk_fma_f32 v[46:47], v[46:47], v[32:33], v[52:53] op_sel_hi:[1,0,1]
	ds_read_b128 v[52:55], v5
	v_mov_b32_e32 v66, v50
	s_add_i32 s0, 0, 0x103f4
	s_waitcnt lgkmcnt(0)
	v_mov_b32_e32 v67, v52
	v_pk_fma_f32 v[66:67], v[66:67], v[0:1], 0 op_sel_hi:[1,0,0]
	v_mov_b32_e32 v52, v51
	v_pk_fma_f32 v[50:51], v[52:53], v[4:5], v[66:67] op_sel_hi:[1,0,1]
	v_mov_b32_e32 v52, v64
	v_mov_b32_e32 v53, v54
	v_pk_fma_f32 v[50:51], v[52:53], v[6:7], v[50:51] op_sel_hi:[1,0,1]
	v_mov_b32_e32 v54, v65
	v_pk_fma_f32 v[50:51], v[54:55], v[8:9], v[50:51] op_sel_hi:[1,0,1]
	v_mov_b32_e32 v52, v56
	v_mov_b32_e32 v53, v60
	v_mov_b32_e32 v5, s0
	s_add_i32 s0, 0, 0x1039c
	v_pk_fma_f32 v[50:51], v[52:53], v[10:11], v[50:51] op_sel_hi:[1,0,1]
	ds_read_b32 v53, v5
	v_mov_b32_e32 v5, s0
	s_add_i32 s0, 0, 0x103a4
	ds_read2_b32 v[54:55], v5 offset1:1
	v_mov_b32_e32 v5, s0
	s_add_i32 s0, 0, 0x103ac
	ds_read2_b32 v[64:65], v5 offset1:1
	v_mov_b32_e32 v5, s0
	s_add_i32 s0, 0, 0x103b4
	ds_read2_b32 v[66:67], v5 offset1:1
	v_mov_b32_e32 v5, s0
	v_mov_b32_e32 v60, v57
	s_add_i32 s0, 0, 0x103dc
	ds_read2_b32 v[68:69], v5 offset1:1
	v_pk_fma_f32 v[50:51], v[60:61], v[12:13], v[50:51] op_sel_hi:[1,0,1]
	v_mov_b32_e32 v56, v58
	v_mov_b32_e32 v57, v62
	v_mov_b32_e32 v5, s0
	v_pk_fma_f32 v[50:51], v[56:57], v[14:15], v[50:51] op_sel_hi:[1,0,1]
	ds_read2_b32 v[56:57], v5 offset1:1
	s_add_i32 s0, 0, 0x103e4
	v_mov_b32_e32 v5, s0
	s_waitcnt lgkmcnt(4)
	v_mov_b32_e32 v58, v54
	s_add_i32 s0, 0, 0x103ec
	s_waitcnt lgkmcnt(0)
	v_mov_b32_e32 v59, v56
	v_mov_b32_e32 v56, v55
	ds_read2_b32 v[54:55], v5 offset1:1
	v_pk_fma_f32 v[50:51], v[58:59], v[16:17], v[50:51] op_sel_hi:[1,0,1]
	v_mov_b32_e32 v5, s0
	v_pk_fma_f32 v[50:51], v[56:57], v[18:19], v[50:51] op_sel_hi:[1,0,1]
	v_mov_b32_e32 v56, v64
	s_waitcnt lgkmcnt(0)
	v_mov_b32_e32 v57, v54
	v_pk_fma_f32 v[50:51], v[56:57], v[20:21], v[50:51] op_sel_hi:[1,0,1]
	v_mov_b32_e32 v54, v65
	v_pk_fma_f32 v[50:51], v[54:55], v[22:23], v[50:51] op_sel_hi:[1,0,1]
	ds_read2_b32 v[54:55], v5 offset1:1
	v_mov_b32_e32 v56, v66
	s_add_i32 s0, 0, 0x103f8
	v_mov_b32_e32 v52, v68
	v_mov_b32_e32 v5, s0
	s_waitcnt lgkmcnt(0)
	v_mov_b32_e32 v57, v54
	v_pk_fma_f32 v[50:51], v[56:57], v[24:25], v[50:51] op_sel_hi:[1,0,1]
	v_mov_b32_e32 v54, v67
	v_pk_fma_f32 v[50:51], v[54:55], v[26:27], v[50:51] op_sel_hi:[1,0,1]
	v_readlane_b32 s0, v252, 56
	v_pk_fma_f32 v[50:51], v[52:53], v[28:29], v[50:51] op_sel_hi:[1,0,1]
	ds_read_b64 v[52:53], v5
	s_add_i32 s0, s0, s82
	v_mov_b32_e32 v54, v69
	s_lshl_b32 s46, s0, 17
	s_lshl_b64 s[0:1], s[46:47], 2
	s_waitcnt lgkmcnt(0)
	v_mov_b32_e32 v55, v52
	v_pk_fma_f32 v[50:51], v[54:55], v[30:31], v[50:51] op_sel_hi:[1,0,1]
	v_mov_b32_e32 v49, v53
	v_pk_fma_f32 v[52:53], v[48:49], v[32:33], v[50:51] op_sel_hi:[1,0,1]
	v_lshl_add_u64 v[50:51], v[2:3], 2, s[0:1]
	v_lshl_add_u64 v[48:49], s[24:25], 0, v[50:51]
	v_lshl_add_u64 v[50:51], s[72:73], 0, v[50:51]
	s_mov_b64 s[0:1], 0
	v_add_co_u32_e32 v152, vcc, 0x20c01000, v48
	s_nop 1
	v_addc_co_u32_e32 v153, vcc, 0, v49, vcc
	v_add_co_u32_e32 v154, vcc, 0x20c03000, v48
	s_nop 1
	v_addc_co_u32_e32 v155, vcc, 0, v49, vcc
	v_add_co_u32_e32 v156, vcc, 0x1000, v50
	s_nop 1
	v_addc_co_u32_e32 v157, vcc, 0, v51, vcc
	v_add_co_u32_e32 v158, vcc, 0x3000, v50
	s_nop 1
	v_addc_co_u32_e32 v159, vcc, 0, v51, vcc
	s_mov_b64 vcc, 0
	v_lshl_add_u64 v[144:145], v[156:157], 0, vcc
	v_lshl_add_u64 v[146:147], v[158:159], 0, vcc
	global_load_dword v112, v[144:145], off offset:-4096
	global_load_dword v113, v[144:145], off offset:-2048
	global_load_dword v114, v[144:145], off
	global_load_dword v115, v[144:145], off offset:2048
	global_load_dword v116, v[146:147], off offset:-4096
	global_load_dword v117, v[146:147], off offset:-2048
	global_load_dword v118, v[146:147], off
	global_load_dword v119, v[146:147], off offset:2048
	s_mov_b64 vcc, 0x4000
	v_lshl_add_u64 v[144:145], v[156:157], 0, vcc
	v_lshl_add_u64 v[146:147], v[158:159], 0, vcc
	global_load_dword v120, v[144:145], off offset:-4096
	global_load_dword v121, v[144:145], off offset:-2048
	global_load_dword v122, v[144:145], off
	global_load_dword v123, v[144:145], off offset:2048
	global_load_dword v124, v[146:147], off offset:-4096
	global_load_dword v125, v[146:147], off offset:-2048
	global_load_dword v126, v[146:147], off
	global_load_dword v127, v[146:147], off offset:2048
; __device__ __forceinline__ void gla_sample_item(Frame& F, int item) {
;     ...
;       for (int chh = 0; chh < 256; ++chh) {
;           const float s0 = S0[(size_t)chh * 512];
;           const f32x4* qp = (const f32x4*)(qT + chh * 16); const f32x4* kp = (const f32x4*)(kT + chh * 16);
;           float sn = dec[chh] * s0;
; #pragma unroll
;           for (int j = 0; j < 4; ++j) { const f32x4 qv = qp[j], kv = kp[j];
; #pragma unroll
;               for (int e = 0; e < 4; ++e) { o[4 * j + e] = fmaf(qv[e], s0, o[4 * j + e]); sn = fmaf(kv[e], v[4 * j + e], sn); } }
;           S1[(size_t)chh * 512] = sn;
;       }
.Lgs_loop:
	s_waitcnt vmcnt(8)
	s_cmp_eq_u32 s0, 0
	s_cbranch_scc1 .Lgs_nost
	global_store_dword v[148:149], v128, off offset:-4096
	global_store_dword v[148:149], v129, off offset:-2048
	global_store_dword v[148:149], v130, off
	global_store_dword v[148:149], v131, off offset:2048
	global_store_dword v[150:151], v132, off offset:-4096
	global_store_dword v[150:151], v133, off offset:-2048
	global_store_dword v[150:151], v134, off
	global_store_dword v[150:151], v135, off offset:2048
.Lgs_nost:
	v_lshl_add_u64 v[148:149], v[152:153], 0, s[0:1]
	v_lshl_add_u64 v[150:151], v[154:155], 0, s[0:1]
	v_mov_b32_e32 v7, s21
	s_add_i32 s22, s2, -4
	v_mov_b32_e32 v5, s22
	ds_read_b128 v[136:139], v5
	ds_read_b128 v[140:143], v5 offset:16
	ds_read_b128 v[58:61], v7
	ds_read_b128 v[62:65], v7 offset:16
	ds_read_b128 v[66:69], v7 offset:32
	ds_read_b128 v[70:73], v7 offset:48
	ds_read_b128 v[74:77], v7 offset:16384
	s_waitcnt lgkmcnt(4)
	v_mul_f32_e32 v128, v112, v136
	v_pk_fma_f32 v[34:35], v[58:59], v[112:113], v[34:35] op_sel_hi:[1,0,1]
	v_pk_fma_f32 v[36:37], v[60:61], v[112:113], v[36:37] op_sel_hi:[1,0,1]
	ds_read_b128 v[58:61], v7 offset:16400
	s_waitcnt lgkmcnt(1)
	v_fmac_f32_e32 v128, v74, v0
	v_fmac_f32_e32 v128, v75, v4
	v_fmac_f32_e32 v128, v76, v6
	v_fmac_f32_e32 v128, v77, v8
	s_waitcnt lgkmcnt(0)
	v_fmac_f32_e32 v128, v58, v10
	v_fmac_f32_e32 v128, v59, v12
	v_fmac_f32_e32 v128, v60, v14
	v_fmac_f32_e32 v128, v61, v16
	ds_read_b128 v[58:61], v7 offset:16416
	v_pk_fma_f32 v[38:39], v[62:63], v[112:113], v[38:39] op_sel_hi:[1,0,1]
	v_pk_fma_f32 v[40:41], v[64:65], v[112:113], v[40:41] op_sel_hi:[1,0,1]
	v_pk_fma_f32 v[42:43], v[66:67], v[112:113], v[42:43] op_sel_hi:[1,0,1]
	v_pk_fma_f32 v[44:45], v[68:69], v[112:113], v[44:45] op_sel_hi:[1,0,1]
	s_waitcnt lgkmcnt(0)
	v_fmac_f32_e32 v128, v58, v18
	v_fmac_f32_e32 v128, v59, v20
	v_fmac_f32_e32 v128, v60, v22
	v_fmac_f32_e32 v128, v61, v24
	ds_read_b128 v[58:61], v7 offset:16432
	v_pk_fma_f32 v[46:47], v[70:71], v[112:113], v[46:47] op_sel_hi:[1,0,1]
	v_pk_fma_f32 v[52:53], v[72:73], v[112:113], v[52:53] op_sel_hi:[1,0,1]
	s_waitcnt lgkmcnt(0)
	v_fmac_f32_e32 v128, v58, v26
	v_fmac_f32_e32 v128, v59, v28
	v_fmac_f32_e32 v128, v60, v30
	v_fmac_f32_e32 v128, v61, v32
	ds_read_b128 v[58:61], v7 offset:64
	ds_read_b128 v[62:65], v7 offset:80
	ds_read_b128 v[66:69], v7 offset:96
	ds_read_b128 v[70:73], v7 offset:112
	ds_read_b128 v[74:77], v7 offset:16448
	s_waitcnt lgkmcnt(4)
	v_mul_f32_e32 v129, v113, v137
	v_pk_fma_f32 v[34:35], v[58:59], v[112:113], v[34:35] op_sel:[0,1,0] op_sel_hi:[1,1,1]
	v_pk_fma_f32 v[36:37], v[60:61], v[112:113], v[36:37] op_sel:[0,1,0] op_sel_hi:[1,1,1]
	ds_read_b128 v[58:61], v7 offset:16464
	s_waitcnt lgkmcnt(1)
	v_fmac_f32_e32 v129, v74, v0
	v_fmac_f32_e32 v129, v75, v4
	v_fmac_f32_e32 v129, v76, v6
	v_fmac_f32_e32 v129, v77, v8
	s_waitcnt lgkmcnt(0)
	v_fmac_f32_e32 v129, v58, v10
	v_fmac_f32_e32 v129, v59, v12
	v_fmac_f32_e32 v129, v60, v14
	v_fmac_f32_e32 v129, v61, v16
	ds_read_b128 v[58:61], v7 offset:16480
	v_pk_fma_f32 v[38:39], v[62:63], v[112:113], v[38:39] op_sel:[0,1,0] op_sel_hi:[1,1,1]
	v_pk_fma_f32 v[40:41], v[64:65], v[112:113], v[40:41] op_sel:[0,1,0] op_sel_hi:[1,1,1]
	v_pk_fma_f32 v[42:43], v[66:67], v[112:113], v[42:43] op_sel:[0,1,0] op_sel_hi:[1,1,1]
	v_pk_fma_f32 v[44:45], v[68:69], v[112:113], v[44:45] op_sel:[0,1,0] op_sel_hi:[1,1,1]
	s_waitcnt lgkmcnt(0)
	v_fmac_f32_e32 v129, v58, v18
	v_fmac_f32_e32 v129, v59, v20
	v_fmac_f32_e32 v129, v60, v22
	v_fmac_f32_e32 v129, v61, v24
	ds_read_b128 v[58:61], v7 offset:16496
	v_pk_fma_f32 v[46:47], v[70:71], v[112:113], v[46:47] op_sel:[0,1,0] op_sel_hi:[1,1,1]
	v_pk_fma_f32 v[52:53], v[72:73], v[112:113], v[52:53] op_sel:[0,1,0] op_sel_hi:[1,1,1]
	s_waitcnt lgkmcnt(0)
	v_fmac_f32_e32 v129, v58, v26
	v_fmac_f32_e32 v129, v59, v28
	v_fmac_f32_e32 v129, v60, v30
	v_fmac_f32_e32 v129, v61, v32
	ds_read_b128 v[58:61], v7 offset:128
	ds_read_b128 v[62:65], v7 offset:144
	ds_read_b128 v[66:69], v7 offset:160
	ds_read_b128 v[70:73], v7 offset:176
	ds_read_b128 v[74:77], v7 offset:16512
	s_waitcnt lgkmcnt(4)
	v_mul_f32_e32 v130, v114, v138
	v_pk_fma_f32 v[34:35], v[58:59], v[114:115], v[34:35] op_sel_hi:[1,0,1]
	v_pk_fma_f32 v[36:37], v[60:61], v[114:115], v[36:37] op_sel_hi:[1,0,1]
	ds_read_b128 v[58:61], v7 offset:16528
	s_waitcnt lgkmcnt(1)
	v_fmac_f32_e32 v130, v74, v0
	v_fmac_f32_e32 v130, v75, v4
	v_fmac_f32_e32 v130, v76, v6
	v_fmac_f32_e32 v130, v77, v8
	s_waitcnt lgkmcnt(0)
	v_fmac_f32_e32 v130, v58, v10
	v_fmac_f32_e32 v130, v59, v12
	v_fmac_f32_e32 v130, v60, v14
	v_fmac_f32_e32 v130, v61, v16
	ds_read_b128 v[58:61], v7 offset:16544
	v_pk_fma_f32 v[38:39], v[62:63], v[114:115], v[38:39] op_sel_hi:[1,0,1]
	v_pk_fma_f32 v[40:41], v[64:65], v[114:115], v[40:41] op_sel_hi:[1,0,1]
	v_pk_fma_f32 v[42:43], v[66:67], v[114:115], v[42:43] op_sel_hi:[1,0,1]
	v_pk_fma_f32 v[44:45], v[68:69], v[114:115], v[44:45] op_sel_hi:[1,0,1]
	s_waitcnt lgkmcnt(0)
	v_fmac_f32_e32 v130, v58, v18
	v_fmac_f32_e32 v130, v59, v20
	v_fmac_f32_e32 v130, v60, v22
	v_fmac_f32_e32 v130, v61, v24
	ds_read_b128 v[58:61], v7 offset:16560
	v_pk_fma_f32 v[46:47], v[70:71], v[114:115], v[46:47] op_sel_hi:[1,0,1]
	v_pk_fma_f32 v[52:53], v[72:73], v[114:115], v[52:53] op_sel_hi:[1,0,1]
	s_waitcnt lgkmcnt(0)
	v_fmac_f32_e32 v130, v58, v26
	v_fmac_f32_e32 v130, v59, v28
	v_fmac_f32_e32 v130, v60, v30
	v_fmac_f32_e32 v130, v61, v32
	ds_read_b128 v[58:61], v7 offset:192
	ds_read_b128 v[62:65], v7 offset:208
	ds_read_b128 v[66:69], v7 offset:224
	ds_read_b128 v[70:73], v7 offset:240
	ds_read_b128 v[74:77], v7 offset:16576
	s_waitcnt lgkmcnt(4)
; __device__ __forceinline__ void gla_sample_item(Frame& F, int item) {
;     ...
;       for (int chh = 0; chh < 256; ++chh) {
;           const float s0 = S0[(size_t)chh * 512];
;           const f32x4* qp = (const f32x4*)(qT + chh * 16); const f32x4* kp = (const f32x4*)(kT + chh * 16);
;           float sn = dec[chh] * s0;
; #pragma unroll
;           for (int j = 0; j < 4; ++j) { const f32x4 qv = qp[j], kv = kp[j];
; #pragma unroll
;               for (int e = 0; e < 4; ++e) { o[4 * j + e] = fmaf(qv[e], s0, o[4 * j + e]); sn = fmaf(kv[e], v[4 * j + e], sn); } }
;           S1[(size_t)chh * 512] = sn;
;       }
	v_mul_f32_e32 v131, v115, v139
	v_pk_fma_f32 v[34:35], v[58:59], v[114:115], v[34:35] op_sel:[0,1,0] op_sel_hi:[1,1,1]
	v_pk_fma_f32 v[36:37], v[60:61], v[114:115], v[36:37] op_sel:[0,1,0] op_sel_hi:[1,1,1]
	ds_read_b128 v[58:61], v7 offset:16592
	s_waitcnt lgkmcnt(1)
	v_fmac_f32_e32 v131, v74, v0
	v_fmac_f32_e32 v131, v75, v4
	v_fmac_f32_e32 v131, v76, v6
	v_fmac_f32_e32 v131, v77, v8
	s_waitcnt lgkmcnt(0)
	v_fmac_f32_e32 v131, v58, v10
	v_fmac_f32_e32 v131, v59, v12
	v_fmac_f32_e32 v131, v60, v14
	v_fmac_f32_e32 v131, v61, v16
	ds_read_b128 v[58:61], v7 offset:16608
	v_pk_fma_f32 v[38:39], v[62:63], v[114:115], v[38:39] op_sel:[0,1,0] op_sel_hi:[1,1,1]
	v_pk_fma_f32 v[40:41], v[64:65], v[114:115], v[40:41] op_sel:[0,1,0] op_sel_hi:[1,1,1]
	v_pk_fma_f32 v[42:43], v[66:67], v[114:115], v[42:43] op_sel:[0,1,0] op_sel_hi:[1,1,1]
	v_pk_fma_f32 v[44:45], v[68:69], v[114:115], v[44:45] op_sel:[0,1,0] op_sel_hi:[1,1,1]
	s_waitcnt lgkmcnt(0)
	v_fmac_f32_e32 v131, v58, v18
	v_fmac_f32_e32 v131, v59, v20
	v_fmac_f32_e32 v131, v60, v22
	v_fmac_f32_e32 v131, v61, v24
	ds_read_b128 v[58:61], v7 offset:16624
	v_pk_fma_f32 v[46:47], v[70:71], v[114:115], v[46:47] op_sel:[0,1,0] op_sel_hi:[1,1,1]
	v_pk_fma_f32 v[52:53], v[72:73], v[114:115], v[52:53] op_sel:[0,1,0] op_sel_hi:[1,1,1]
	s_waitcnt lgkmcnt(0)
	v_fmac_f32_e32 v131, v58, v26
	v_fmac_f32_e32 v131, v59, v28
	v_fmac_f32_e32 v131, v60, v30
	v_fmac_f32_e32 v131, v61, v32
	ds_read_b128 v[58:61], v7 offset:256
	ds_read_b128 v[62:65], v7 offset:272
	ds_read_b128 v[66:69], v7 offset:288
	ds_read_b128 v[70:73], v7 offset:304
	ds_read_b128 v[74:77], v7 offset:16640
	s_waitcnt lgkmcnt(4)
	v_mul_f32_e32 v132, v116, v140
	v_pk_fma_f32 v[34:35], v[58:59], v[116:117], v[34:35] op_sel_hi:[1,0,1]
	v_pk_fma_f32 v[36:37], v[60:61], v[116:117], v[36:37] op_sel_hi:[1,0,1]
	ds_read_b128 v[58:61], v7 offset:16656
	s_waitcnt lgkmcnt(1)
	v_fmac_f32_e32 v132, v74, v0
	v_fmac_f32_e32 v132, v75, v4
	v_fmac_f32_e32 v132, v76, v6
	v_fmac_f32_e32 v132, v77, v8
	s_waitcnt lgkmcnt(0)
	v_fmac_f32_e32 v132, v58, v10
	v_fmac_f32_e32 v132, v59, v12
	v_fmac_f32_e32 v132, v60, v14
	v_fmac_f32_e32 v132, v61, v16
	ds_read_b128 v[58:61], v7 offset:16672
	v_pk_fma_f32 v[38:39], v[62:63], v[116:117], v[38:39] op_sel_hi:[1,0,1]
	v_pk_fma_f32 v[40:41], v[64:65], v[116:117], v[40:41] op_sel_hi:[1,0,1]
	v_pk_fma_f32 v[42:43], v[66:67], v[116:117], v[42:43] op_sel_hi:[1,0,1]
	v_pk_fma_f32 v[44:45], v[68:69], v[116:117], v[44:45] op_sel_hi:[1,0,1]
	s_waitcnt lgkmcnt(0)
	v_fmac_f32_e32 v132, v58, v18
	v_fmac_f32_e32 v132, v59, v20
	v_fmac_f32_e32 v132, v60, v22
	v_fmac_f32_e32 v132, v61, v24
	ds_read_b128 v[58:61], v7 offset:16688
	v_pk_fma_f32 v[46:47], v[70:71], v[116:117], v[46:47] op_sel_hi:[1,0,1]
	v_pk_fma_f32 v[52:53], v[72:73], v[116:117], v[52:53] op_sel_hi:[1,0,1]
	s_waitcnt lgkmcnt(0)
	v_fmac_f32_e32 v132, v58, v26
	v_fmac_f32_e32 v132, v59, v28
	v_fmac_f32_e32 v132, v60, v30
	v_fmac_f32_e32 v132, v61, v32
	ds_read_b128 v[58:61], v7 offset:320
	ds_read_b128 v[62:65], v7 offset:336
	ds_read_b128 v[66:69], v7 offset:352
	ds_read_b128 v[70:73], v7 offset:368
	ds_read_b128 v[74:77], v7 offset:16704
	s_waitcnt lgkmcnt(4)
	v_mul_f32_e32 v133, v117, v141
	v_pk_fma_f32 v[34:35], v[58:59], v[116:117], v[34:35] op_sel:[0,1,0] op_sel_hi:[1,1,1]
	v_pk_fma_f32 v[36:37], v[60:61], v[116:117], v[36:37] op_sel:[0,1,0] op_sel_hi:[1,1,1]
	ds_read_b128 v[58:61], v7 offset:16720
	s_waitcnt lgkmcnt(1)
	v_fmac_f32_e32 v133, v74, v0
	v_fmac_f32_e32 v133, v75, v4
	v_fmac_f32_e32 v133, v76, v6
	v_fmac_f32_e32 v133, v77, v8
	s_waitcnt lgkmcnt(0)
	v_fmac_f32_e32 v133, v58, v10
	v_fmac_f32_e32 v133, v59, v12
	v_fmac_f32_e32 v133, v60, v14
	v_fmac_f32_e32 v133, v61, v16
	ds_read_b128 v[58:61], v7 offset:16736
	v_pk_fma_f32 v[38:39], v[62:63], v[116:117], v[38:39] op_sel:[0,1,0] op_sel_hi:[1,1,1]
	v_pk_fma_f32 v[40:41], v[64:65], v[116:117], v[40:41] op_sel:[0,1,0] op_sel_hi:[1,1,1]
	v_pk_fma_f32 v[42:43], v[66:67], v[116:117], v[42:43] op_sel:[0,1,0] op_sel_hi:[1,1,1]
	v_pk_fma_f32 v[44:45], v[68:69], v[116:117], v[44:45] op_sel:[0,1,0] op_sel_hi:[1,1,1]
	s_waitcnt lgkmcnt(0)
	v_fmac_f32_e32 v133, v58, v18
	v_fmac_f32_e32 v133, v59, v20
	v_fmac_f32_e32 v133, v60, v22
	v_fmac_f32_e32 v133, v61, v24
	ds_read_b128 v[58:61], v7 offset:16752
	v_pk_fma_f32 v[46:47], v[70:71], v[116:117], v[46:47] op_sel:[0,1,0] op_sel_hi:[1,1,1]
	v_pk_fma_f32 v[52:53], v[72:73], v[116:117], v[52:53] op_sel:[0,1,0] op_sel_hi:[1,1,1]
	s_waitcnt lgkmcnt(0)
	v_fmac_f32_e32 v133, v58, v26
	v_fmac_f32_e32 v133, v59, v28
	v_fmac_f32_e32 v133, v60, v30
	v_fmac_f32_e32 v133, v61, v32
	ds_read_b128 v[58:61], v7 offset:384
	ds_read_b128 v[62:65], v7 offset:400
	ds_read_b128 v[66:69], v7 offset:416
	ds_read_b128 v[70:73], v7 offset:432
	ds_read_b128 v[74:77], v7 offset:16768
	s_waitcnt lgkmcnt(4)
	v_mul_f32_e32 v134, v118, v142
	v_pk_fma_f32 v[34:35], v[58:59], v[118:119], v[34:35] op_sel_hi:[1,0,1]
	v_pk_fma_f32 v[36:37], v[60:61], v[118:119], v[36:37] op_sel_hi:[1,0,1]
	ds_read_b128 v[58:61], v7 offset:16784
	s_waitcnt lgkmcnt(1)
	v_fmac_f32_e32 v134, v74, v0
	v_fmac_f32_e32 v134, v75, v4
	v_fmac_f32_e32 v134, v76, v6
	v_fmac_f32_e32 v134, v77, v8
	s_waitcnt lgkmcnt(0)
	v_fmac_f32_e32 v134, v58, v10
	v_fmac_f32_e32 v134, v59, v12
	v_fmac_f32_e32 v134, v60, v14
	v_fmac_f32_e32 v134, v61, v16
	ds_read_b128 v[58:61], v7 offset:16800
	v_pk_fma_f32 v[38:39], v[62:63], v[118:119], v[38:39] op_sel_hi:[1,0,1]
	v_pk_fma_f32 v[40:41], v[64:65], v[118:119], v[40:41] op_sel_hi:[1,0,1]
	v_pk_fma_f32 v[42:43], v[66:67], v[118:119], v[42:43] op_sel_hi:[1,0,1]
	v_pk_fma_f32 v[44:45], v[68:69], v[118:119], v[44:45] op_sel_hi:[1,0,1]
	s_waitcnt lgkmcnt(0)
; __device__ __forceinline__ void gla_sample_item(Frame& F, int item) {
;     ...
;       for (int chh = 0; chh < 256; ++chh) {
;           const float s0 = S0[(size_t)chh * 512];
;           const f32x4* qp = (const f32x4*)(qT + chh * 16); const f32x4* kp = (const f32x4*)(kT + chh * 16);
;           float sn = dec[chh] * s0;
; #pragma unroll
;           for (int j = 0; j < 4; ++j) { const f32x4 qv = qp[j], kv = kp[j];
; #pragma unroll
;               for (int e = 0; e < 4; ++e) { o[4 * j + e] = fmaf(qv[e], s0, o[4 * j + e]); sn = fmaf(kv[e], v[4 * j + e], sn); } }
;           S1[(size_t)chh * 512] = sn;
;       }
	v_fmac_f32_e32 v134, v58, v18
	v_fmac_f32_e32 v134, v59, v20
	v_fmac_f32_e32 v134, v60, v22
	v_fmac_f32_e32 v134, v61, v24
	ds_read_b128 v[58:61], v7 offset:16816
	v_pk_fma_f32 v[46:47], v[70:71], v[118:119], v[46:47] op_sel_hi:[1,0,1]
	v_pk_fma_f32 v[52:53], v[72:73], v[118:119], v[52:53] op_sel_hi:[1,0,1]
	s_waitcnt lgkmcnt(0)
	v_fmac_f32_e32 v134, v58, v26
	v_fmac_f32_e32 v134, v59, v28
	v_fmac_f32_e32 v134, v60, v30
	v_fmac_f32_e32 v134, v61, v32
	ds_read_b128 v[58:61], v7 offset:448
	ds_read_b128 v[62:65], v7 offset:464
	ds_read_b128 v[66:69], v7 offset:480
	ds_read_b128 v[70:73], v7 offset:496
	ds_read_b128 v[74:77], v7 offset:16832
	s_waitcnt lgkmcnt(4)
	v_mul_f32_e32 v135, v119, v143
	v_pk_fma_f32 v[34:35], v[58:59], v[118:119], v[34:35] op_sel:[0,1,0] op_sel_hi:[1,1,1]
	v_pk_fma_f32 v[36:37], v[60:61], v[118:119], v[36:37] op_sel:[0,1,0] op_sel_hi:[1,1,1]
	ds_read_b128 v[58:61], v7 offset:16848
	s_waitcnt lgkmcnt(1)
	v_fmac_f32_e32 v135, v74, v0
	v_fmac_f32_e32 v135, v75, v4
	v_fmac_f32_e32 v135, v76, v6
	v_fmac_f32_e32 v135, v77, v8
	s_waitcnt lgkmcnt(0)
	v_fmac_f32_e32 v135, v58, v10
	v_fmac_f32_e32 v135, v59, v12
	v_fmac_f32_e32 v135, v60, v14
	v_fmac_f32_e32 v135, v61, v16
	ds_read_b128 v[58:61], v7 offset:16864
	v_pk_fma_f32 v[38:39], v[62:63], v[118:119], v[38:39] op_sel:[0,1,0] op_sel_hi:[1,1,1]
	v_pk_fma_f32 v[40:41], v[64:65], v[118:119], v[40:41] op_sel:[0,1,0] op_sel_hi:[1,1,1]
	v_pk_fma_f32 v[42:43], v[66:67], v[118:119], v[42:43] op_sel:[0,1,0] op_sel_hi:[1,1,1]
	v_pk_fma_f32 v[44:45], v[68:69], v[118:119], v[44:45] op_sel:[0,1,0] op_sel_hi:[1,1,1]
	s_waitcnt lgkmcnt(0)
	v_fmac_f32_e32 v135, v58, v18
	v_fmac_f32_e32 v135, v59, v20
	v_fmac_f32_e32 v135, v60, v22
	v_fmac_f32_e32 v135, v61, v24
	ds_read_b128 v[58:61], v7 offset:16880
	v_pk_fma_f32 v[46:47], v[70:71], v[118:119], v[46:47] op_sel:[0,1,0] op_sel_hi:[1,1,1]
	v_pk_fma_f32 v[52:53], v[72:73], v[118:119], v[52:53] op_sel:[0,1,0] op_sel_hi:[1,1,1]
	s_waitcnt lgkmcnt(0)
	v_fmac_f32_e32 v135, v58, v26
	v_fmac_f32_e32 v135, v59, v28
	v_fmac_f32_e32 v135, v60, v30
	v_fmac_f32_e32 v135, v61, v32
	s_cmp_gt_u32 s0, 0x74000
	s_cbranch_scc1 .Lgs_nold0
	s_add_u32 vcc_lo, s0, 0x8000
	s_addc_u32 vcc_hi, s1, 0
	v_lshl_add_u64 v[144:145], v[156:157], 0, vcc
	v_lshl_add_u64 v[146:147], v[158:159], 0, vcc
	global_load_dword v112, v[144:145], off offset:-4096
	global_load_dword v113, v[144:145], off offset:-2048
	global_load_dword v114, v[144:145], off
	global_load_dword v115, v[144:145], off offset:2048
	global_load_dword v116, v[146:147], off offset:-4096
	global_load_dword v117, v[146:147], off offset:-2048
	global_load_dword v118, v[146:147], off
	global_load_dword v119, v[146:147], off offset:2048
.Lgs_nold0:
	s_add_u32 s0, s0, 0x4000
	s_addc_u32 s1, s1, 0
	s_addk_i32 s21, 0x200
	s_add_i32 s2, s2, 32
	s_cmp_eq_u32 s0, 0x7c000
	s_cbranch_scc0 .Lgs_w1
	s_waitcnt vmcnt(0)
.Lgs_w1:
	s_waitcnt vmcnt(8)
	global_store_dword v[148:149], v128, off offset:-4096
	global_store_dword v[148:149], v129, off offset:-2048
	global_store_dword v[148:149], v130, off
	global_store_dword v[148:149], v131, off offset:2048
	global_store_dword v[150:151], v132, off offset:-4096
	global_store_dword v[150:151], v133, off offset:-2048
	global_store_dword v[150:151], v134, off
	global_store_dword v[150:151], v135, off offset:2048
	v_lshl_add_u64 v[148:149], v[152:153], 0, s[0:1]
	v_lshl_add_u64 v[150:151], v[154:155], 0, s[0:1]
	v_mov_b32_e32 v7, s21
	s_add_i32 s22, s2, -4
	v_mov_b32_e32 v5, s22
	ds_read_b128 v[136:139], v5
	ds_read_b128 v[140:143], v5 offset:16
	ds_read_b128 v[58:61], v7
	ds_read_b128 v[62:65], v7 offset:16
	ds_read_b128 v[66:69], v7 offset:32
	ds_read_b128 v[70:73], v7 offset:48
	ds_read_b128 v[74:77], v7 offset:16384
	s_waitcnt lgkmcnt(4)
	v_mul_f32_e32 v128, v120, v136
	v_pk_fma_f32 v[34:35], v[58:59], v[120:121], v[34:35] op_sel_hi:[1,0,1]
	v_pk_fma_f32 v[36:37], v[60:61], v[120:121], v[36:37] op_sel_hi:[1,0,1]
	ds_read_b128 v[58:61], v7 offset:16400
	s_waitcnt lgkmcnt(1)
	v_fmac_f32_e32 v128, v74, v0
	v_fmac_f32_e32 v128, v75, v4
	v_fmac_f32_e32 v128, v76, v6
	v_fmac_f32_e32 v128, v77, v8
	s_waitcnt lgkmcnt(0)
	v_fmac_f32_e32 v128, v58, v10
	v_fmac_f32_e32 v128, v59, v12
	v_fmac_f32_e32 v128, v60, v14
	v_fmac_f32_e32 v128, v61, v16
	ds_read_b128 v[58:61], v7 offset:16416
	v_pk_fma_f32 v[38:39], v[62:63], v[120:121], v[38:39] op_sel_hi:[1,0,1]
	v_pk_fma_f32 v[40:41], v[64:65], v[120:121], v[40:41] op_sel_hi:[1,0,1]
	v_pk_fma_f32 v[42:43], v[66:67], v[120:121], v[42:43] op_sel_hi:[1,0,1]
	v_pk_fma_f32 v[44:45], v[68:69], v[120:121], v[44:45] op_sel_hi:[1,0,1]
	s_waitcnt lgkmcnt(0)
	v_fmac_f32_e32 v128, v58, v18
	v_fmac_f32_e32 v128, v59, v20
	v_fmac_f32_e32 v128, v60, v22
	v_fmac_f32_e32 v128, v61, v24
	ds_read_b128 v[58:61], v7 offset:16432
	v_pk_fma_f32 v[46:47], v[70:71], v[120:121], v[46:47] op_sel_hi:[1,0,1]
	v_pk_fma_f32 v[52:53], v[72:73], v[120:121], v[52:53] op_sel_hi:[1,0,1]
	s_waitcnt lgkmcnt(0)
	v_fmac_f32_e32 v128, v58, v26
	v_fmac_f32_e32 v128, v59, v28
	v_fmac_f32_e32 v128, v60, v30
	v_fmac_f32_e32 v128, v61, v32
	ds_read_b128 v[58:61], v7 offset:64
	ds_read_b128 v[62:65], v7 offset:80
	ds_read_b128 v[66:69], v7 offset:96
	ds_read_b128 v[70:73], v7 offset:112
	ds_read_b128 v[74:77], v7 offset:16448
	s_waitcnt lgkmcnt(4)
	v_mul_f32_e32 v129, v121, v137
	v_pk_fma_f32 v[34:35], v[58:59], v[120:121], v[34:35] op_sel:[0,1,0] op_sel_hi:[1,1,1]
	v_pk_fma_f32 v[36:37], v[60:61], v[120:121], v[36:37] op_sel:[0,1,0] op_sel_hi:[1,1,1]
	ds_read_b128 v[58:61], v7 offset:16464
	s_waitcnt lgkmcnt(1)
	v_fmac_f32_e32 v129, v74, v0
	v_fmac_f32_e32 v129, v75, v4
	v_fmac_f32_e32 v129, v76, v6
	v_fmac_f32_e32 v129, v77, v8
	s_waitcnt lgkmcnt(0)
; __device__ __forceinline__ void gla_sample_item(Frame& F, int item) {
;     ...
;       for (int chh = 0; chh < 256; ++chh) {
;           const float s0 = S0[(size_t)chh * 512];
;           const f32x4* qp = (const f32x4*)(qT + chh * 16); const f32x4* kp = (const f32x4*)(kT + chh * 16);
;           float sn = dec[chh] * s0;
; #pragma unroll
;           for (int j = 0; j < 4; ++j) { const f32x4 qv = qp[j], kv = kp[j];
; #pragma unroll
;               for (int e = 0; e < 4; ++e) { o[4 * j + e] = fmaf(qv[e], s0, o[4 * j + e]); sn = fmaf(kv[e], v[4 * j + e], sn); } }
;           S1[(size_t)chh * 512] = sn;
;       }
	v_fmac_f32_e32 v129, v58, v10
	v_fmac_f32_e32 v129, v59, v12
	v_fmac_f32_e32 v129, v60, v14
	v_fmac_f32_e32 v129, v61, v16
	ds_read_b128 v[58:61], v7 offset:16480
	v_pk_fma_f32 v[38:39], v[62:63], v[120:121], v[38:39] op_sel:[0,1,0] op_sel_hi:[1,1,1]
	v_pk_fma_f32 v[40:41], v[64:65], v[120:121], v[40:41] op_sel:[0,1,0] op_sel_hi:[1,1,1]
	v_pk_fma_f32 v[42:43], v[66:67], v[120:121], v[42:43] op_sel:[0,1,0] op_sel_hi:[1,1,1]
	v_pk_fma_f32 v[44:45], v[68:69], v[120:121], v[44:45] op_sel:[0,1,0] op_sel_hi:[1,1,1]
	s_waitcnt lgkmcnt(0)
	v_fmac_f32_e32 v129, v58, v18
	v_fmac_f32_e32 v129, v59, v20
	v_fmac_f32_e32 v129, v60, v22
	v_fmac_f32_e32 v129, v61, v24
	ds_read_b128 v[58:61], v7 offset:16496
	v_pk_fma_f32 v[46:47], v[70:71], v[120:121], v[46:47] op_sel:[0,1,0] op_sel_hi:[1,1,1]
	v_pk_fma_f32 v[52:53], v[72:73], v[120:121], v[52:53] op_sel:[0,1,0] op_sel_hi:[1,1,1]
	s_waitcnt lgkmcnt(0)
	v_fmac_f32_e32 v129, v58, v26
	v_fmac_f32_e32 v129, v59, v28
	v_fmac_f32_e32 v129, v60, v30
	v_fmac_f32_e32 v129, v61, v32
	ds_read_b128 v[58:61], v7 offset:128
	ds_read_b128 v[62:65], v7 offset:144
	ds_read_b128 v[66:69], v7 offset:160
	ds_read_b128 v[70:73], v7 offset:176
	ds_read_b128 v[74:77], v7 offset:16512
	s_waitcnt lgkmcnt(4)
	v_mul_f32_e32 v130, v122, v138
	v_pk_fma_f32 v[34:35], v[58:59], v[122:123], v[34:35] op_sel_hi:[1,0,1]
	v_pk_fma_f32 v[36:37], v[60:61], v[122:123], v[36:37] op_sel_hi:[1,0,1]
	ds_read_b128 v[58:61], v7 offset:16528
	s_waitcnt lgkmcnt(1)
	v_fmac_f32_e32 v130, v74, v0
	v_fmac_f32_e32 v130, v75, v4
	v_fmac_f32_e32 v130, v76, v6
	v_fmac_f32_e32 v130, v77, v8
	s_waitcnt lgkmcnt(0)
	v_fmac_f32_e32 v130, v58, v10
	v_fmac_f32_e32 v130, v59, v12
	v_fmac_f32_e32 v130, v60, v14
	v_fmac_f32_e32 v130, v61, v16
	ds_read_b128 v[58:61], v7 offset:16544
	v_pk_fma_f32 v[38:39], v[62:63], v[122:123], v[38:39] op_sel_hi:[1,0,1]
	v_pk_fma_f32 v[40:41], v[64:65], v[122:123], v[40:41] op_sel_hi:[1,0,1]
	v_pk_fma_f32 v[42:43], v[66:67], v[122:123], v[42:43] op_sel_hi:[1,0,1]
	v_pk_fma_f32 v[44:45], v[68:69], v[122:123], v[44:45] op_sel_hi:[1,0,1]
	s_waitcnt lgkmcnt(0)
	v_fmac_f32_e32 v130, v58, v18
	v_fmac_f32_e32 v130, v59, v20
	v_fmac_f32_e32 v130, v60, v22
	v_fmac_f32_e32 v130, v61, v24
	ds_read_b128 v[58:61], v7 offset:16560
	v_pk_fma_f32 v[46:47], v[70:71], v[122:123], v[46:47] op_sel_hi:[1,0,1]
	v_pk_fma_f32 v[52:53], v[72:73], v[122:123], v[52:53] op_sel_hi:[1,0,1]
	s_waitcnt lgkmcnt(0)
	v_fmac_f32_e32 v130, v58, v26
	v_fmac_f32_e32 v130, v59, v28
	v_fmac_f32_e32 v130, v60, v30
	v_fmac_f32_e32 v130, v61, v32
	ds_read_b128 v[58:61], v7 offset:192
	ds_read_b128 v[62:65], v7 offset:208
	ds_read_b128 v[66:69], v7 offset:224
	ds_read_b128 v[70:73], v7 offset:240
	ds_read_b128 v[74:77], v7 offset:16576
	s_waitcnt lgkmcnt(4)
	v_mul_f32_e32 v131, v123, v139
	v_pk_fma_f32 v[34:35], v[58:59], v[122:123], v[34:35] op_sel:[0,1,0] op_sel_hi:[1,1,1]
	v_pk_fma_f32 v[36:37], v[60:61], v[122:123], v[36:37] op_sel:[0,1,0] op_sel_hi:[1,1,1]
	ds_read_b128 v[58:61], v7 offset:16592
	s_waitcnt lgkmcnt(1)
	v_fmac_f32_e32 v131, v74, v0
	v_fmac_f32_e32 v131, v75, v4
	v_fmac_f32_e32 v131, v76, v6
	v_fmac_f32_e32 v131, v77, v8
	s_waitcnt lgkmcnt(0)
	v_fmac_f32_e32 v131, v58, v10
	v_fmac_f32_e32 v131, v59, v12
	v_fmac_f32_e32 v131, v60, v14
	v_fmac_f32_e32 v131, v61, v16
	ds_read_b128 v[58:61], v7 offset:16608
	v_pk_fma_f32 v[38:39], v[62:63], v[122:123], v[38:39] op_sel:[0,1,0] op_sel_hi:[1,1,1]
	v_pk_fma_f32 v[40:41], v[64:65], v[122:123], v[40:41] op_sel:[0,1,0] op_sel_hi:[1,1,1]
	v_pk_fma_f32 v[42:43], v[66:67], v[122:123], v[42:43] op_sel:[0,1,0] op_sel_hi:[1,1,1]
	v_pk_fma_f32 v[44:45], v[68:69], v[122:123], v[44:45] op_sel:[0,1,0] op_sel_hi:[1,1,1]
	s_waitcnt lgkmcnt(0)
	v_fmac_f32_e32 v131, v58, v18
	v_fmac_f32_e32 v131, v59, v20
	v_fmac_f32_e32 v131, v60, v22
	v_fmac_f32_e32 v131, v61, v24
	ds_read_b128 v[58:61], v7 offset:16624
	v_pk_fma_f32 v[46:47], v[70:71], v[122:123], v[46:47] op_sel:[0,1,0] op_sel_hi:[1,1,1]
	v_pk_fma_f32 v[52:53], v[72:73], v[122:123], v[52:53] op_sel:[0,1,0] op_sel_hi:[1,1,1]
	s_waitcnt lgkmcnt(0)
	v_fmac_f32_e32 v131, v58, v26
	v_fmac_f32_e32 v131, v59, v28
	v_fmac_f32_e32 v131, v60, v30
	v_fmac_f32_e32 v131, v61, v32
	ds_read_b128 v[58:61], v7 offset:256
	ds_read_b128 v[62:65], v7 offset:272
	ds_read_b128 v[66:69], v7 offset:288
	ds_read_b128 v[70:73], v7 offset:304
	ds_read_b128 v[74:77], v7 offset:16640
	s_waitcnt lgkmcnt(4)
	v_mul_f32_e32 v132, v124, v140
	v_pk_fma_f32 v[34:35], v[58:59], v[124:125], v[34:35] op_sel_hi:[1,0,1]
	v_pk_fma_f32 v[36:37], v[60:61], v[124:125], v[36:37] op_sel_hi:[1,0,1]
	ds_read_b128 v[58:61], v7 offset:16656
	s_waitcnt lgkmcnt(1)
	v_fmac_f32_e32 v132, v74, v0
	v_fmac_f32_e32 v132, v75, v4
	v_fmac_f32_e32 v132, v76, v6
	v_fmac_f32_e32 v132, v77, v8
	s_waitcnt lgkmcnt(0)
	v_fmac_f32_e32 v132, v58, v10
	v_fmac_f32_e32 v132, v59, v12
	v_fmac_f32_e32 v132, v60, v14
	v_fmac_f32_e32 v132, v61, v16
	ds_read_b128 v[58:61], v7 offset:16672
	v_pk_fma_f32 v[38:39], v[62:63], v[124:125], v[38:39] op_sel_hi:[1,0,1]
	v_pk_fma_f32 v[40:41], v[64:65], v[124:125], v[40:41] op_sel_hi:[1,0,1]
	v_pk_fma_f32 v[42:43], v[66:67], v[124:125], v[42:43] op_sel_hi:[1,0,1]
	v_pk_fma_f32 v[44:45], v[68:69], v[124:125], v[44:45] op_sel_hi:[1,0,1]
	s_waitcnt lgkmcnt(0)
	v_fmac_f32_e32 v132, v58, v18
	v_fmac_f32_e32 v132, v59, v20
	v_fmac_f32_e32 v132, v60, v22
	v_fmac_f32_e32 v132, v61, v24
	ds_read_b128 v[58:61], v7 offset:16688
	v_pk_fma_f32 v[46:47], v[70:71], v[124:125], v[46:47] op_sel_hi:[1,0,1]
	v_pk_fma_f32 v[52:53], v[72:73], v[124:125], v[52:53] op_sel_hi:[1,0,1]
	s_waitcnt lgkmcnt(0)
; __device__ __forceinline__ void gla_sample_item(Frame& F, int item) {
;     ...
;       for (int chh = 0; chh < 256; ++chh) {
;           const float s0 = S0[(size_t)chh * 512];
;           const f32x4* qp = (const f32x4*)(qT + chh * 16); const f32x4* kp = (const f32x4*)(kT + chh * 16);
;           float sn = dec[chh] * s0;
; #pragma unroll
;           for (int j = 0; j < 4; ++j) { const f32x4 qv = qp[j], kv = kp[j];
; #pragma unroll
;               for (int e = 0; e < 4; ++e) { o[4 * j + e] = fmaf(qv[e], s0, o[4 * j + e]); sn = fmaf(kv[e], v[4 * j + e], sn); } }
;           S1[(size_t)chh * 512] = sn;
;       }
	v_fmac_f32_e32 v132, v58, v26
	v_fmac_f32_e32 v132, v59, v28
	v_fmac_f32_e32 v132, v60, v30
	v_fmac_f32_e32 v132, v61, v32
	ds_read_b128 v[58:61], v7 offset:320
	ds_read_b128 v[62:65], v7 offset:336
	ds_read_b128 v[66:69], v7 offset:352
	ds_read_b128 v[70:73], v7 offset:368
	ds_read_b128 v[74:77], v7 offset:16704
	s_waitcnt lgkmcnt(4)
	v_mul_f32_e32 v133, v125, v141
	v_pk_fma_f32 v[34:35], v[58:59], v[124:125], v[34:35] op_sel:[0,1,0] op_sel_hi:[1,1,1]
	v_pk_fma_f32 v[36:37], v[60:61], v[124:125], v[36:37] op_sel:[0,1,0] op_sel_hi:[1,1,1]
	ds_read_b128 v[58:61], v7 offset:16720
	s_waitcnt lgkmcnt(1)
	v_fmac_f32_e32 v133, v74, v0
	v_fmac_f32_e32 v133, v75, v4
	v_fmac_f32_e32 v133, v76, v6
	v_fmac_f32_e32 v133, v77, v8
	s_waitcnt lgkmcnt(0)
	v_fmac_f32_e32 v133, v58, v10
	v_fmac_f32_e32 v133, v59, v12
	v_fmac_f32_e32 v133, v60, v14
	v_fmac_f32_e32 v133, v61, v16
	ds_read_b128 v[58:61], v7 offset:16736
	v_pk_fma_f32 v[38:39], v[62:63], v[124:125], v[38:39] op_sel:[0,1,0] op_sel_hi:[1,1,1]
	v_pk_fma_f32 v[40:41], v[64:65], v[124:125], v[40:41] op_sel:[0,1,0] op_sel_hi:[1,1,1]
	v_pk_fma_f32 v[42:43], v[66:67], v[124:125], v[42:43] op_sel:[0,1,0] op_sel_hi:[1,1,1]
	v_pk_fma_f32 v[44:45], v[68:69], v[124:125], v[44:45] op_sel:[0,1,0] op_sel_hi:[1,1,1]
	s_waitcnt lgkmcnt(0)
	v_fmac_f32_e32 v133, v58, v18
	v_fmac_f32_e32 v133, v59, v20
	v_fmac_f32_e32 v133, v60, v22
	v_fmac_f32_e32 v133, v61, v24
	ds_read_b128 v[58:61], v7 offset:16752
	v_pk_fma_f32 v[46:47], v[70:71], v[124:125], v[46:47] op_sel:[0,1,0] op_sel_hi:[1,1,1]
	v_pk_fma_f32 v[52:53], v[72:73], v[124:125], v[52:53] op_sel:[0,1,0] op_sel_hi:[1,1,1]
	s_waitcnt lgkmcnt(0)
	v_fmac_f32_e32 v133, v58, v26
	v_fmac_f32_e32 v133, v59, v28
	v_fmac_f32_e32 v133, v60, v30
	v_fmac_f32_e32 v133, v61, v32
	ds_read_b128 v[58:61], v7 offset:384
	ds_read_b128 v[62:65], v7 offset:400
	ds_read_b128 v[66:69], v7 offset:416
	ds_read_b128 v[70:73], v7 offset:432
	ds_read_b128 v[74:77], v7 offset:16768
	s_waitcnt lgkmcnt(4)
	v_mul_f32_e32 v134, v126, v142
	v_pk_fma_f32 v[34:35], v[58:59], v[126:127], v[34:35] op_sel_hi:[1,0,1]
	v_pk_fma_f32 v[36:37], v[60:61], v[126:127], v[36:37] op_sel_hi:[1,0,1]
	ds_read_b128 v[58:61], v7 offset:16784
	s_waitcnt lgkmcnt(1)
	v_fmac_f32_e32 v134, v74, v0
	v_fmac_f32_e32 v134, v75, v4
	v_fmac_f32_e32 v134, v76, v6
	v_fmac_f32_e32 v134, v77, v8
	s_waitcnt lgkmcnt(0)
	v_fmac_f32_e32 v134, v58, v10
	v_fmac_f32_e32 v134, v59, v12
	v_fmac_f32_e32 v134, v60, v14
	v_fmac_f32_e32 v134, v61, v16
	ds_read_b128 v[58:61], v7 offset:16800
	v_pk_fma_f32 v[38:39], v[62:63], v[126:127], v[38:39] op_sel_hi:[1,0,1]
	v_pk_fma_f32 v[40:41], v[64:65], v[126:127], v[40:41] op_sel_hi:[1,0,1]
	v_pk_fma_f32 v[42:43], v[66:67], v[126:127], v[42:43] op_sel_hi:[1,0,1]
	v_pk_fma_f32 v[44:45], v[68:69], v[126:127], v[44:45] op_sel_hi:[1,0,1]
	s_waitcnt lgkmcnt(0)
	v_fmac_f32_e32 v134, v58, v18
	v_fmac_f32_e32 v134, v59, v20
	v_fmac_f32_e32 v134, v60, v22
	v_fmac_f32_e32 v134, v61, v24
	ds_read_b128 v[58:61], v7 offset:16816
	v_pk_fma_f32 v[46:47], v[70:71], v[126:127], v[46:47] op_sel_hi:[1,0,1]
	v_pk_fma_f32 v[52:53], v[72:73], v[126:127], v[52:53] op_sel_hi:[1,0,1]
	s_waitcnt lgkmcnt(0)
	v_fmac_f32_e32 v134, v58, v26
	v_fmac_f32_e32 v134, v59, v28
	v_fmac_f32_e32 v134, v60, v30
	v_fmac_f32_e32 v134, v61, v32
	ds_read_b128 v[58:61], v7 offset:448
	ds_read_b128 v[62:65], v7 offset:464
	ds_read_b128 v[66:69], v7 offset:480
	ds_read_b128 v[70:73], v7 offset:496
	ds_read_b128 v[74:77], v7 offset:16832
	s_waitcnt lgkmcnt(4)
	v_mul_f32_e32 v135, v127, v143
	v_pk_fma_f32 v[34:35], v[58:59], v[126:127], v[34:35] op_sel:[0,1,0] op_sel_hi:[1,1,1]
	v_pk_fma_f32 v[36:37], v[60:61], v[126:127], v[36:37] op_sel:[0,1,0] op_sel_hi:[1,1,1]
	ds_read_b128 v[58:61], v7 offset:16848
	s_waitcnt lgkmcnt(1)
	v_fmac_f32_e32 v135, v74, v0
	v_fmac_f32_e32 v135, v75, v4
	v_fmac_f32_e32 v135, v76, v6
	v_fmac_f32_e32 v135, v77, v8
	s_waitcnt lgkmcnt(0)
	v_fmac_f32_e32 v135, v58, v10
	v_fmac_f32_e32 v135, v59, v12
	v_fmac_f32_e32 v135, v60, v14
	v_fmac_f32_e32 v135, v61, v16
	ds_read_b128 v[58:61], v7 offset:16864
	v_pk_fma_f32 v[38:39], v[62:63], v[126:127], v[38:39] op_sel:[0,1,0] op_sel_hi:[1,1,1]
	v_pk_fma_f32 v[40:41], v[64:65], v[126:127], v[40:41] op_sel:[0,1,0] op_sel_hi:[1,1,1]
	v_pk_fma_f32 v[42:43], v[66:67], v[126:127], v[42:43] op_sel:[0,1,0] op_sel_hi:[1,1,1]
	v_pk_fma_f32 v[44:45], v[68:69], v[126:127], v[44:45] op_sel:[0,1,0] op_sel_hi:[1,1,1]
	s_waitcnt lgkmcnt(0)
	v_fmac_f32_e32 v135, v58, v18
	v_fmac_f32_e32 v135, v59, v20
	v_fmac_f32_e32 v135, v60, v22
	v_fmac_f32_e32 v135, v61, v24
	ds_read_b128 v[58:61], v7 offset:16880
	v_pk_fma_f32 v[46:47], v[70:71], v[126:127], v[46:47] op_sel:[0,1,0] op_sel_hi:[1,1,1]
	v_pk_fma_f32 v[52:53], v[72:73], v[126:127], v[52:53] op_sel:[0,1,0] op_sel_hi:[1,1,1]
	s_waitcnt lgkmcnt(0)
	v_fmac_f32_e32 v135, v58, v26
	v_fmac_f32_e32 v135, v59, v28
	v_fmac_f32_e32 v135, v60, v30
	v_fmac_f32_e32 v135, v61, v32
	s_cmp_gt_u32 s0, 0x74000
	s_cbranch_scc1 .Lgs_nold1
	s_add_u32 vcc_lo, s0, 0x8000
	s_addc_u32 vcc_hi, s1, 0
	v_lshl_add_u64 v[144:145], v[156:157], 0, vcc
	v_lshl_add_u64 v[146:147], v[158:159], 0, vcc
	global_load_dword v120, v[144:145], off offset:-4096
	global_load_dword v121, v[144:145], off offset:-2048
	global_load_dword v122, v[144:145], off
	global_load_dword v123, v[144:145], off offset:2048
	global_load_dword v124, v[146:147], off offset:-4096
	global_load_dword v125, v[146:147], off offset:-2048
	global_load_dword v126, v[146:147], off
	global_load_dword v127, v[146:147], off offset:2048
; __device__ __forceinline__ unsigned f2bf(float f) { unsigned u = __builtin_bit_cast(unsigned, f); return (u + 0x7fffu + ((u >> 16) & 1u)) >> 16; }
; __device__ __forceinline__ void gla_sample_item(Frame& F, int item) {
;     ...
;       for (int chh = 0; chh < 256; ++chh) {
;           const float s0 = S0[(size_t)chh * 512];
;           const f32x4* qp = (const f32x4*)(qT + chh * 16); const f32x4* kp = (const f32x4*)(kT + chh * 16);
;           float sn = dec[chh] * s0;
; #pragma unroll
;           for (int j = 0; j < 4; ++j) { const f32x4 qv = qp[j], kv = kp[j];
; #pragma unroll
;               for (int e = 0; e < 4; ++e) { o[4 * j + e] = fmaf(qv[e], s0, o[4 * j + e]); sn = fmaf(kv[e], v[4 * j + e], sn); } }
;           S1[(size_t)chh * 512] = sn;
;       }
; #pragma unroll
;       for (int ti = 0; ti < 16; ++ti) MIXIN[(size_t)(m0 + ti) * 4096 + 2048 + h * 512 + dv] = (unsigned short)f2bf(o[ti]);
.Lgs_nold1:
	s_add_u32 s0, s0, 0x4000
	s_addc_u32 s1, s1, 0
	s_addk_i32 s21, 0x200
	s_add_i32 s2, s2, 32
	s_cmp_lg_u32 s0, 0x80000
	s_cbranch_scc1 .Lgs_loop
	global_store_dword v[148:149], v128, off offset:-4096
	global_store_dword v[148:149], v129, off offset:-2048
	global_store_dword v[148:149], v130, off
	global_store_dword v[148:149], v131, off offset:2048
	global_store_dword v[150:151], v132, off offset:-4096
	global_store_dword v[150:151], v133, off offset:-2048
	global_store_dword v[150:151], v134, off
	global_store_dword v[150:151], v135, off offset:2048
	s_lshl_b32 s1, s8, 13
	s_lshl_b32 s0, s6, 1
	v_readlane_b32 s24, v253, 32
	s_or_b32 s1, s1, s0
	v_readlane_b32 s26, v253, 34
	v_readlane_b32 s27, v253, 35
	s_add_u32 s22, s26, s1
	s_addc_u32 s23, s27, 0
	s_lshl_b32 s1, s14, 13
	v_lshlrev_b64 v[2:3], 1, v[2:3]
	s_or_b32 s1, s1, s0
	v_lshl_add_u64 v[4:5], s[22:23], 0, v[2:3]
	s_add_u32 s22, s26, s1
	v_bfe_u32 v0, v34, 16, 1
	v_add_co_u32_e32 v4, vcc, 0x2f401000, v4
	s_addc_u32 s23, s27, 0
	s_lshl_b32 s1, s13, 13
	v_add3_u32 v0, v34, v0, s42
	v_addc_co_u32_e32 v5, vcc, 0, v5, vcc
	s_or_b32 s1, s1, s0
	global_store_short_d16_hi v[4:5], v0, off
	v_lshl_add_u64 v[4:5], s[22:23], 0, v[2:3]
	s_mov_b32 s2, 0x2f401000
	s_add_u32 s22, s26, s1
	v_bfe_u32 v0, v35, 16, 1
	v_add_co_u32_e32 v4, vcc, s2, v4
	s_addc_u32 s23, s27, 0
	s_lshl_b32 s1, s12, 13
	v_add3_u32 v0, v35, v0, s42
	v_addc_co_u32_e32 v5, vcc, 0, v5, vcc
	s_or_b32 s1, s1, s0
	global_store_short_d16_hi v[4:5], v0, off
	v_lshl_add_u64 v[4:5], s[22:23], 0, v[2:3]
	s_add_u32 s12, s26, s1
	v_bfe_u32 v0, v36, 16, 1
	v_add_co_u32_e32 v4, vcc, s2, v4
	s_addc_u32 s13, s27, 0
	s_lshl_b32 s1, s11, 13
	v_add3_u32 v0, v36, v0, s42
	v_addc_co_u32_e32 v5, vcc, 0, v5, vcc
	s_or_b32 s1, s1, s0
	global_store_short_d16_hi v[4:5], v0, off
	v_lshl_add_u64 v[4:5], s[12:13], 0, v[2:3]
	s_add_u32 s12, s26, s1
	v_bfe_u32 v0, v37, 16, 1
	v_add_co_u32_e32 v4, vcc, s2, v4
	s_addc_u32 s13, s27, 0
	s_lshl_b32 s1, s7, 13
	v_add3_u32 v0, v37, v0, s42
	v_addc_co_u32_e32 v5, vcc, 0, v5, vcc
	s_or_b32 s1, s1, s0
	global_store_short_d16_hi v[4:5], v0, off
	v_lshl_add_u64 v[4:5], s[12:13], 0, v[2:3]
	s_add_u32 s6, s26, s1
	v_bfe_u32 v0, v38, 16, 1
	v_add_co_u32_e32 v4, vcc, s2, v4
	s_addc_u32 s7, s27, 0
	s_lshl_b32 s1, s5, 13
	v_add3_u32 v0, v38, v0, s42
	v_addc_co_u32_e32 v5, vcc, 0, v5, vcc
	s_or_b32 s1, s1, s0
	global_store_short_d16_hi v[4:5], v0, off
	v_lshl_add_u64 v[4:5], s[6:7], 0, v[2:3]
	s_add_u32 s6, s26, s1
	v_bfe_u32 v0, v39, 16, 1
	v_add_co_u32_e32 v4, vcc, s2, v4
	s_addc_u32 s7, s27, 0
	s_lshl_b32 s1, s4, 13
	v_add3_u32 v0, v39, v0, s42
	v_addc_co_u32_e32 v5, vcc, 0, v5, vcc
	s_or_b32 s1, s1, s0
	global_store_short_d16_hi v[4:5], v0, off
	v_lshl_add_u64 v[4:5], s[6:7], 0, v[2:3]
	s_add_u32 s4, s26, s1
	v_bfe_u32 v0, v40, 16, 1
	v_add_co_u32_e32 v4, vcc, s2, v4
	s_addc_u32 s5, s27, 0
	s_lshl_b32 s1, s20, 13
	v_add3_u32 v0, v40, v0, s42
	v_addc_co_u32_e32 v5, vcc, 0, v5, vcc
	s_or_b32 s1, s1, s0
	global_store_short_d16_hi v[4:5], v0, off
	v_lshl_add_u64 v[4:5], s[4:5], 0, v[2:3]
	s_add_u32 s4, s26, s1
	v_bfe_u32 v0, v41, 16, 1
	v_add_co_u32_e32 v4, vcc, s2, v4
	s_addc_u32 s5, s27, 0
	s_lshl_b32 s1, s19, 13
	v_add3_u32 v0, v41, v0, s42
	v_addc_co_u32_e32 v5, vcc, 0, v5, vcc
	s_or_b32 s1, s1, s0
	global_store_short_d16_hi v[4:5], v0, off
	v_lshl_add_u64 v[4:5], s[4:5], 0, v[2:3]
	s_add_u32 s4, s26, s1
	v_bfe_u32 v0, v42, 16, 1
	v_add_co_u32_e32 v4, vcc, s2, v4
	s_addc_u32 s5, s27, 0
	s_lshl_b32 s1, s18, 13
	v_add3_u32 v0, v42, v0, s42
	v_addc_co_u32_e32 v5, vcc, 0, v5, vcc
	s_or_b32 s1, s1, s0
	global_store_short_d16_hi v[4:5], v0, off
	v_lshl_add_u64 v[4:5], s[4:5], 0, v[2:3]
	s_add_u32 s4, s26, s1
	v_bfe_u32 v0, v43, 16, 1
	v_add_co_u32_e32 v4, vcc, s2, v4
	s_addc_u32 s5, s27, 0
	s_lshl_b32 s1, s17, 13
	v_add3_u32 v0, v43, v0, s42
	v_addc_co_u32_e32 v5, vcc, 0, v5, vcc
	s_or_b32 s1, s1, s0
	global_store_short_d16_hi v[4:5], v0, off
	v_lshl_add_u64 v[4:5], s[4:5], 0, v[2:3]
	s_add_u32 s4, s26, s1
	v_bfe_u32 v0, v44, 16, 1
	v_add_co_u32_e32 v4, vcc, s2, v4
	s_addc_u32 s5, s27, 0
	s_lshl_b32 s1, s16, 13
	v_add3_u32 v0, v44, v0, s42
	v_addc_co_u32_e32 v5, vcc, 0, v5, vcc
	s_or_b32 s1, s1, s0
	global_store_short_d16_hi v[4:5], v0, off
	v_lshl_add_u64 v[4:5], s[4:5], 0, v[2:3]
	s_add_u32 s4, s26, s1
	v_bfe_u32 v0, v45, 16, 1
	v_add_co_u32_e32 v4, vcc, s2, v4
	s_addc_u32 s5, s27, 0
	s_lshl_b32 s1, s15, 13
	v_add3_u32 v0, v45, v0, s42
	v_addc_co_u32_e32 v5, vcc, 0, v5, vcc
	s_or_b32 s1, s1, s0
	global_store_short_d16_hi v[4:5], v0, off
	v_lshl_add_u64 v[4:5], s[4:5], 0, v[2:3]
	s_add_u32 s4, s26, s1
	v_bfe_u32 v0, v46, 16, 1
	v_add_co_u32_e32 v4, vcc, s2, v4
	s_addc_u32 s5, s27, 0
	s_lshl_b32 s1, s10, 13
	v_add3_u32 v0, v46, v0, s42
	v_addc_co_u32_e32 v5, vcc, 0, v5, vcc
	s_or_b32 s1, s1, s0
	global_store_short_d16_hi v[4:5], v0, off
	v_lshl_add_u64 v[4:5], s[4:5], 0, v[2:3]
	s_add_u32 s4, s26, s1
	v_bfe_u32 v0, v47, 16, 1
	v_add_co_u32_e32 v4, vcc, s2, v4
	s_addc_u32 s5, s27, 0
	s_lshl_b32 s1, s9, 13
	v_add3_u32 v0, v47, v0, s42
	v_addc_co_u32_e32 v5, vcc, 0, v5, vcc
	s_or_b32 s0, s1, s0
	global_store_short_d16_hi v[4:5], v0, off
	v_lshl_add_u64 v[4:5], s[4:5], 0, v[2:3]
	s_add_u32 s0, s26, s0
	v_bfe_u32 v0, v52, 16, 1
	v_add_co_u32_e32 v4, vcc, s2, v4
	s_addc_u32 s1, s27, 0
	v_add3_u32 v0, v52, v0, s42
	v_addc_co_u32_e32 v5, vcc, 0, v5, vcc
	v_lshl_add_u64 v[2:3], s[0:1], 0, v[2:3]
	global_store_short_d16_hi v[4:5], v0, off
	v_bfe_u32 v0, v53, 16, 1
	v_add_co_u32_e32 v2, vcc, 0x2f401000, v2
	v_add3_u32 v0, v53, v0, s42
	s_nop 0
	v_addc_co_u32_e32 v3, vcc, 0, v3, vcc
	s_mov_b64 s[0:1], 0
	v_readlane_b32 s25, v253, 33
	global_store_short_d16_hi v[2:3], v0, off
